# residual epilogues: one 64-lane atomic per 64 rows (8 -> 2 row-sum atomics per wave and unit), exec-mask blocks removed
# baseline (speedup 1.0000x reference)
; __device__ __forceinline__ u32x4 pack8(f32x4 a, f32x4 b) { u32x4 w; w.x = cvt_pk_bf16(a[0], a[1]); w.y = cvt_pk_bf16(a[2], a[3]); w.z = cvt_pk_bf16(b[0], b[1]); w.w = cvt_pk_bf16(b[2], b[3]); return w; }
;     __device__ __forceinline__ void operator()(const f32x4 (&acc)[2][2][4][2], const Unit& u, int wr, int wc, int fr, int fq) const {
;         const int row0 = u.pm * BM + wr * 64 + fr, col = u.pn * BM + wc * 64 + 8 * fq;
; #pragma unroll
;         for (int ai = 0; ai < 2; ++ai)
; #pragma unroll
;             for (int m = 0; m < 4; ++m) {
;                 const int row = row0 + ai * HALF + m * 16; const size_t off = (size_t)row * 2048 + col;
;                 float s = 0.f;
; #pragma unroll
;                 for (int bj = 0; bj < 2; ++bj) {
;                     f32x4 b0, b1;
;                     if (BASE_F32) { const float* bp = (const float*)base + off + bj * 32; b0 = *(const f32x4*)bp; b1 = *(const f32x4*)(bp + 4); }
;                     else { const u32x4 w = *(const u32x4*)((const bf16_t*)base + off + bj * 32);
;                         b0 = (f32x4){__uint_as_float(w.x << 16), __uint_as_float(w.x & 0xffff0000u), __uint_as_float(w.y << 16), __uint_as_float(w.y & 0xffff0000u)};
;                         b1 = (f32x4){__uint_as_float(w.z << 16), __uint_as_float(w.z & 0xffff0000u), __uint_as_float(w.w << 16), __uint_as_float(w.w & 0xffff0000u)}; }
;                     const f32x4 h0 = b0 + acc[ai][bj][m][0], h1 = b1 + acc[ai][bj][m][1];
;                     s += (h0[0] * h0[0] + h0[1] * h0[1]) + (h0[2] * h0[2] + h0[3] * h0[3]) + (h1[0] * h1[0] + h1[1] * h1[1]) + (h1[2] * h1[2] + h1[3] * h1[3]);
;                     *(u32x4*)(H + off + bj * 32) = pack8(h0, h1);
;                 }
;                 s += __shfl_xor(s, 16); s += __shfl_xor(s, 32);
.LBB0_331:
	v_lshl_add_u32 v136, s22, 8, v138
	v_ashrrev_i32_e32 v137, 31, v136
	v_lshl_or_b32 v134, s24, 8, v140
	v_lshlrev_b64 v[142:143], 12, v[136:137]
	v_ashrrev_i32_e32 v135, 31, v134
	v_lshl_add_u64 v[142:143], s[6:7], 0, v[142:143]
	v_lshl_add_u64 v[146:147], v[134:135], 1, v[142:143]
	v_mov_b32_e32 v168, v136
	v_ashrrev_i32_e32 v169, 31, v168
	v_lshlrev_b64 v[168:169], 12, v[168:169]
	v_lshl_add_u64 v[168:169], s[6:7], 0, v[168:169]
	v_lshl_add_u64 v[168:169], v[134:135], 1, v[168:169]
	global_load_dwordx4 v[152:155], v[168:169], off
	global_load_dwordx4 v[156:159], v[168:169], off offset:64
	v_add_u32_e32 v168, 0x10, v136
	v_ashrrev_i32_e32 v169, 31, v168
	v_lshlrev_b64 v[168:169], 12, v[168:169]
	v_lshl_add_u64 v[168:169], s[6:7], 0, v[168:169]
	v_lshl_add_u64 v[168:169], v[134:135], 1, v[168:169]
	global_load_dwordx4 v[160:163], v[168:169], off
	global_load_dwordx4 v[164:167], v[168:169], off offset:64
	v_add_u32_e32 v168, 0x20, v136
	v_ashrrev_i32_e32 v169, 31, v168
	v_lshlrev_b64 v[168:169], 12, v[168:169]
	v_lshl_add_u64 v[168:169], s[6:7], 0, v[168:169]
	v_lshl_add_u64 v[168:169], v[134:135], 1, v[168:169]
	global_load_dwordx4 v[178:181], v[168:169], off
	global_load_dwordx4 v[182:185], v[168:169], off offset:64
	v_add_u32_e32 v168, 0x30, v136
	v_ashrrev_i32_e32 v169, 31, v168
	v_lshlrev_b64 v[168:169], 12, v[168:169]
	v_lshl_add_u64 v[168:169], s[6:7], 0, v[168:169]
	v_lshl_add_u64 v[168:169], v[134:135], 1, v[168:169]
	global_load_dwordx4 v[186:189], v[168:169], off
	global_load_dwordx4 v[190:193], v[168:169], off offset:64
	v_add_u32_e32 v168, 0x80, v136
	v_ashrrev_i32_e32 v169, 31, v168
	v_lshlrev_b64 v[168:169], 12, v[168:169]
	v_lshl_add_u64 v[168:169], s[6:7], 0, v[168:169]
	v_lshl_add_u64 v[168:169], v[134:135], 1, v[168:169]
	global_load_dwordx4 v[194:197], v[168:169], off
	global_load_dwordx4 v[198:201], v[168:169], off offset:64
	v_add_u32_e32 v168, 0x90, v136
	v_ashrrev_i32_e32 v169, 31, v168
	v_lshlrev_b64 v[168:169], 12, v[168:169]
	v_lshl_add_u64 v[168:169], s[6:7], 0, v[168:169]
	v_lshl_add_u64 v[168:169], v[134:135], 1, v[168:169]
	global_load_dwordx4 v[212:215], v[168:169], off
	global_load_dwordx4 v[216:219], v[168:169], off offset:64
	v_and_b32_e32 v230, 48, v209
	v_add_u32_e32 v230, v230, v136
	v_mov_b32_e32 v231, 0
	v_lshl_add_u64 v[230:231], v[230:231], 2, s[8:9]
	s_nop 1
	s_waitcnt vmcnt(11)
	v_mov_b32_e32 v142, v152
	v_mov_b32_e32 v143, v153
	v_mov_b32_e32 v144, v154
	v_mov_b32_e32 v145, v155
	s_nop 0
	v_lshlrev_b32_e32 v148, 16, v142
	v_and_b32_e32 v149, 0xffff0000, v142
	v_lshlrev_b32_e32 v142, 16, v143
	v_and_b32_e32 v143, 0xffff0000, v143
	v_lshlrev_b32_e32 v150, 16, v144
	v_and_b32_e32 v151, 0xffff0000, v144
	v_lshlrev_b32_e32 v144, 16, v145
	v_and_b32_e32 v145, 0xffff0000, v145
	v_pk_add_f32 v[126:127], v[126:127], v[142:143]
	v_pk_add_f32 v[124:125], v[124:125], v[148:149]
	v_pk_add_f32 v[142:143], v[122:123], v[144:145]
	v_pk_add_f32 v[122:123], v[120:121], v[150:151]
	v_mul_f32_e32 v120, v125, v125
	v_mul_f32_e32 v121, v127, v127
	v_fmac_f32_e32 v120, v124, v124
	v_fmac_f32_e32 v121, v126, v126
	v_add_f32_e32 v120, v120, v121
	v_mul_f32_e32 v121, v123, v123
	v_fmac_f32_e32 v121, v122, v122
	v_add_f32_e32 v120, v121, v120
	v_mul_f32_e32 v121, v143, v143
	v_fmac_f32_e32 v121, v142, v142
	v_add_f32_e32 v144, v121, v120
	v_cvt_pk_bf16_f32 v120, v124, v125
	v_cvt_pk_bf16_f32 v121, v126, v127
	v_cvt_pk_bf16_f32 v122, v122, v123
	v_cvt_pk_bf16_f32 v123, v142, v143
	global_store_dwordx4 v[146:147], v[120:123], off
	s_nop 1
	s_waitcnt vmcnt(11)
	v_mov_b32_e32 v120, v156
	v_mov_b32_e32 v121, v157
	v_mov_b32_e32 v122, v158
	v_mov_b32_e32 v123, v159
	v_add_u32_e32 v168, 0xa0, v136
	v_ashrrev_i32_e32 v169, 31, v168
	v_lshlrev_b64 v[168:169], 12, v[168:169]
	v_lshl_add_u64 v[168:169], s[6:7], 0, v[168:169]
	v_lshl_add_u64 v[168:169], v[134:135], 1, v[168:169]
	global_load_dwordx4 v[152:155], v[168:169], off
	global_load_dwordx4 v[156:159], v[168:169], off offset:64
	s_nop 0
	v_lshlrev_b32_e32 v124, 16, v120
	v_and_b32_e32 v125, 0xffff0000, v120
	v_lshlrev_b32_e32 v120, 16, v121
	v_and_b32_e32 v121, 0xffff0000, v121
	v_lshlrev_b32_e32 v126, 16, v122
	v_and_b32_e32 v127, 0xffff0000, v122
	v_lshlrev_b32_e32 v122, 16, v123
	v_and_b32_e32 v123, 0xffff0000, v123
	v_pk_add_f32 v[118:119], v[118:119], v[120:121]
	v_pk_add_f32 v[116:117], v[116:117], v[124:125]
	v_pk_add_f32 v[120:121], v[114:115], v[122:123]
	v_pk_add_f32 v[114:115], v[112:113], v[126:127]
	v_mul_f32_e32 v112, v117, v117
	v_mul_f32_e32 v113, v119, v119
	v_fmac_f32_e32 v112, v116, v116
	v_fmac_f32_e32 v113, v118, v118
	v_add_f32_e32 v112, v112, v113
	v_mul_f32_e32 v113, v115, v115
	v_fmac_f32_e32 v113, v114, v114
	v_add_f32_e32 v112, v113, v112
	v_mul_f32_e32 v113, v121, v121
	v_fmac_f32_e32 v113, v120, v120
	v_add_f32_e32 v112, v113, v112
	v_add_f32_e32 v122, v144, v112
	v_cvt_pk_bf16_f32 v112, v116, v117
	v_cvt_pk_bf16_f32 v113, v118, v119
	v_cvt_pk_bf16_f32 v114, v114, v115
	v_cvt_pk_bf16_f32 v115, v120, v121
	global_store_dwordx4 v[146:147], v[112:115], off offset:64
	s_nop 1
	v_and_b32_e32 v113, 64, v209
	v_xor_b32_e32 v112, 16, v209
	v_add_u32_e32 v113, 64, v113
	v_cmp_lt_i32_e32 vcc, v112, v113
	v_xor_b32_e32 v115, 32, v209
	s_nop 0
	v_cndmask_b32_e32 v112, v209, v112, vcc
	v_lshlrev_b32_e32 v114, 2, v112
	ds_bpermute_b32 v112, v114, v122
	v_cmp_lt_i32_e32 vcc, v115, v113
	s_waitcnt lgkmcnt(0)
	v_add_f32_e32 v112, v122, v112
	v_cndmask_b32_e32 v113, v209, v115, vcc
	v_lshlrev_b32_e32 v115, 2, v113
	ds_bpermute_b32 v113, v115, v112
	s_waitcnt lgkmcnt(0)
	v_add_f32_e32 v112, v112, v113
	v_mov_b32_e32 v229, v112
; __device__ __forceinline__ u32x4 pack8(f32x4 a, f32x4 b) { u32x4 w; w.x = cvt_pk_bf16(a[0], a[1]); w.y = cvt_pk_bf16(a[2], a[3]); w.z = cvt_pk_bf16(b[0], b[1]); w.w = cvt_pk_bf16(b[2], b[3]); return w; }
;     __device__ __forceinline__ void operator()(const f32x4 (&acc)[2][2][4][2], const Unit& u, int wr, int wc, int fr, int fq) const {
;     ...
;                 const int row = row0 + ai * HALF + m * 16; const size_t off = (size_t)row * 2048 + col;
;                 float s = 0.f;
; #pragma unroll
;                 for (int bj = 0; bj < 2; ++bj) {
;                     f32x4 b0, b1;
;                     if (BASE_F32) { const float* bp = (const float*)base + off + bj * 32; b0 = *(const f32x4*)bp; b1 = *(const f32x4*)(bp + 4); }
;                     else { const u32x4 w = *(const u32x4*)((const bf16_t*)base + off + bj * 32);
;                         b0 = (f32x4){__uint_as_float(w.x << 16), __uint_as_float(w.x & 0xffff0000u), __uint_as_float(w.y << 16), __uint_as_float(w.y & 0xffff0000u)};
;                         b1 = (f32x4){__uint_as_float(w.z << 16), __uint_as_float(w.z & 0xffff0000u), __uint_as_float(w.w << 16), __uint_as_float(w.w & 0xffff0000u)}; }
;                     const f32x4 h0 = b0 + acc[ai][bj][m][0], h1 = b1 + acc[ai][bj][m][1];
;                     s += (h0[0] * h0[0] + h0[1] * h0[1]) + (h0[2] * h0[2] + h0[3] * h0[3]) + (h1[0] * h1[0] + h1[1] * h1[1]) + (h1[2] * h1[2] + h1[3] * h1[3]);
;                     *(u32x4*)(H + off + bj * 32) = pack8(h0, h1);
;                 }
;                 s += __shfl_xor(s, 16); s += __shfl_xor(s, 32);
;                 if (fq == 0) __hip_atomic_fetch_add(ss + row, s, __ATOMIC_RELAXED, __HIP_MEMORY_SCOPE_AGENT);
.LBB0_333:
	v_or_b32_e32 v112, 16, v136
	s_waitcnt lgkmcnt(0)
	v_ashrrev_i32_e32 v113, 31, v112
	v_lshlrev_b64 v[116:117], 12, v[112:113]
	v_lshl_add_u64 v[116:117], s[6:7], 0, v[116:117]
	v_lshl_add_u64 v[120:121], v[134:135], 1, v[116:117]
	s_nop 1
	s_waitcnt vmcnt(13)
	v_mov_b32_e32 v116, v160
	v_mov_b32_e32 v117, v161
	v_mov_b32_e32 v118, v162
	v_mov_b32_e32 v119, v163
	s_nop 0
	v_lshlrev_b32_e32 v122, 16, v116
	v_and_b32_e32 v123, 0xffff0000, v116
	v_lshlrev_b32_e32 v116, 16, v117
	v_and_b32_e32 v117, 0xffff0000, v117
	v_lshlrev_b32_e32 v124, 16, v118
	v_and_b32_e32 v125, 0xffff0000, v118
	v_lshlrev_b32_e32 v118, 16, v119
	v_and_b32_e32 v119, 0xffff0000, v119
	v_pk_add_f32 v[116:117], v[110:111], v[116:117]
	v_pk_add_f32 v[122:123], v[108:109], v[122:123]
	v_pk_add_f32 v[118:119], v[106:107], v[118:119]
	v_pk_add_f32 v[124:125], v[104:105], v[124:125]
	v_cvt_pk_bf16_f32 v104, v122, v123
	v_cvt_pk_bf16_f32 v105, v116, v117
	v_mul_f32_e32 v123, v123, v123
	v_cvt_pk_bf16_f32 v106, v124, v125
	v_cvt_pk_bf16_f32 v107, v118, v119
	s_nop 1
	s_waitcnt vmcnt(12)
	v_mov_b32_e32 v108, v164
	v_mov_b32_e32 v109, v165
	v_mov_b32_e32 v110, v166
	v_mov_b32_e32 v111, v167
	v_add_u32_e32 v168, 0xb0, v136
	v_ashrrev_i32_e32 v169, 31, v168
	v_lshlrev_b64 v[168:169], 12, v[168:169]
	v_lshl_add_u64 v[168:169], s[6:7], 0, v[168:169]
	v_lshl_add_u64 v[168:169], v[134:135], 1, v[168:169]
	global_load_dwordx4 v[160:163], v[168:169], off
	global_load_dwordx4 v[164:167], v[168:169], off offset:64
	v_mul_f32_e32 v117, v117, v117
	v_mul_f32_e32 v125, v125, v125
	v_fmac_f32_e32 v123, v122, v122
	v_fmac_f32_e32 v117, v116, v116
	v_mul_f32_e32 v119, v119, v119
	v_fmac_f32_e32 v125, v124, v124
	v_add_f32_e32 v116, v123, v117
	v_fmac_f32_e32 v119, v118, v118
	v_add_f32_e32 v116, v125, v116
	v_add_f32_e32 v122, v119, v116
	global_store_dwordx4 v[120:121], v[104:107], off
	s_nop 0
	v_lshlrev_b32_e32 v116, 16, v108
	v_and_b32_e32 v117, 0xffff0000, v108
	v_lshlrev_b32_e32 v108, 16, v109
	v_and_b32_e32 v109, 0xffff0000, v109
	v_lshlrev_b32_e32 v118, 16, v110
	v_and_b32_e32 v119, 0xffff0000, v110
	v_lshlrev_b32_e32 v110, 16, v111
	v_and_b32_e32 v111, 0xffff0000, v111
	v_pk_add_f32 v[102:103], v[102:103], v[108:109]
	v_pk_add_f32 v[100:101], v[100:101], v[116:117]
	v_pk_add_f32 v[108:109], v[98:99], v[110:111]
	v_pk_add_f32 v[110:111], v[96:97], v[118:119]
	v_mul_f32_e32 v96, v101, v101
	v_mul_f32_e32 v97, v103, v103
	v_mul_f32_e32 v98, v111, v111
	v_fmac_f32_e32 v96, v100, v100
	v_fmac_f32_e32 v97, v102, v102
	v_mul_f32_e32 v99, v109, v109
	v_fmac_f32_e32 v98, v110, v110
	v_add_f32_e32 v96, v96, v97
	v_add_f32_e32 v96, v98, v96
	v_fmac_f32_e32 v99, v108, v108
	v_add_f32_e32 v96, v99, v96
	v_add_f32_e32 v96, v122, v96
	ds_bpermute_b32 v97, v114, v96
	v_cvt_pk_bf16_f32 v98, v100, v101
	v_cvt_pk_bf16_f32 v99, v102, v103
	v_cvt_pk_bf16_f32 v100, v110, v111
	v_cvt_pk_bf16_f32 v101, v108, v109
	s_waitcnt lgkmcnt(0)
	v_add_f32_e32 v96, v96, v97
	ds_bpermute_b32 v97, v115, v96
	global_store_dwordx4 v[120:121], v[98:101], off offset:64
	s_waitcnt lgkmcnt(0)
	v_add_f32_e32 v96, v96, v97
	s_mov_b32 s22, 0xffff0000
	s_mov_b32 s23, 0
	v_cndmask_b32_e64 v229, v229, v96, s[22:23]
.LBB0_335:
	v_or_b32_e32 v96, 32, v136
	s_waitcnt lgkmcnt(0)
	v_ashrrev_i32_e32 v97, 31, v96
	v_lshlrev_b64 v[98:99], 12, v[96:97]
	v_lshl_add_u64 v[98:99], s[6:7], 0, v[98:99]
	v_lshl_add_u64 v[102:103], v[134:135], 1, v[98:99]
	s_nop 1
	s_waitcnt vmcnt(15)
	v_mov_b32_e32 v98, v178
	v_mov_b32_e32 v99, v179
	v_mov_b32_e32 v100, v180
	v_mov_b32_e32 v101, v181
	s_nop 0
	v_lshlrev_b32_e32 v104, 16, v98
	v_and_b32_e32 v105, 0xffff0000, v98
	v_lshlrev_b32_e32 v98, 16, v99
	v_and_b32_e32 v99, 0xffff0000, v99
	v_lshlrev_b32_e32 v106, 16, v100
	v_and_b32_e32 v107, 0xffff0000, v100
	v_lshlrev_b32_e32 v100, 16, v101
	v_and_b32_e32 v101, 0xffff0000, v101
	v_pk_add_f32 v[98:99], v[94:95], v[98:99]
	v_pk_add_f32 v[104:105], v[92:93], v[104:105]
	v_pk_add_f32 v[100:101], v[90:91], v[100:101]
	v_pk_add_f32 v[106:107], v[88:89], v[106:107]
	v_cvt_pk_bf16_f32 v88, v104, v105
	v_cvt_pk_bf16_f32 v89, v98, v99
	v_mul_f32_e32 v105, v105, v105
	v_cvt_pk_bf16_f32 v90, v106, v107
	v_cvt_pk_bf16_f32 v91, v100, v101
	s_nop 1
	s_waitcnt vmcnt(14)
	v_mov_b32_e32 v92, v182
	v_mov_b32_e32 v93, v183
	v_mov_b32_e32 v94, v184
	v_mov_b32_e32 v95, v185
	v_mul_f32_e32 v99, v99, v99
	v_mul_f32_e32 v107, v107, v107
	v_fmac_f32_e32 v105, v104, v104
	v_fmac_f32_e32 v99, v98, v98
	v_mul_f32_e32 v101, v101, v101
	v_fmac_f32_e32 v107, v106, v106
	v_add_f32_e32 v98, v105, v99
	v_fmac_f32_e32 v101, v100, v100
	v_add_f32_e32 v98, v107, v98
	v_add_f32_e32 v104, v101, v98
	global_store_dwordx4 v[102:103], v[88:91], off
	s_nop 0
	v_lshlrev_b32_e32 v98, 16, v92
	v_and_b32_e32 v99, 0xffff0000, v92
	v_lshlrev_b32_e32 v92, 16, v93
	v_and_b32_e32 v93, 0xffff0000, v93
	v_lshlrev_b32_e32 v100, 16, v94
	v_and_b32_e32 v101, 0xffff0000, v94
	v_lshlrev_b32_e32 v94, 16, v95
	v_and_b32_e32 v95, 0xffff0000, v95
	v_pk_add_f32 v[86:87], v[86:87], v[92:93]
	v_pk_add_f32 v[84:85], v[84:85], v[98:99]
	v_pk_add_f32 v[92:93], v[82:83], v[94:95]
	v_pk_add_f32 v[94:95], v[80:81], v[100:101]
	v_mul_f32_e32 v80, v85, v85
	v_mul_f32_e32 v81, v87, v87
	v_mul_f32_e32 v82, v95, v95
	v_fmac_f32_e32 v80, v84, v84
	v_fmac_f32_e32 v81, v86, v86
	v_mul_f32_e32 v83, v93, v93
	v_fmac_f32_e32 v82, v94, v94
	v_add_f32_e32 v80, v80, v81
	v_add_f32_e32 v80, v82, v80
	v_fmac_f32_e32 v83, v92, v92
	v_add_f32_e32 v80, v83, v80
	v_add_f32_e32 v80, v104, v80
	ds_bpermute_b32 v81, v114, v80
	v_cvt_pk_bf16_f32 v82, v84, v85
	v_cvt_pk_bf16_f32 v83, v86, v87
	v_cvt_pk_bf16_f32 v84, v94, v95
	v_cvt_pk_bf16_f32 v85, v92, v93
	s_waitcnt lgkmcnt(0)
	v_add_f32_e32 v80, v80, v81
	ds_bpermute_b32 v81, v115, v80
	global_store_dwordx4 v[102:103], v[82:85], off offset:64
	s_waitcnt lgkmcnt(0)
	v_add_f32_e32 v80, v80, v81
	s_mov_b32 s22, 0
	s_mov_b32 s23, 0xffff
	v_cndmask_b32_e64 v229, v229, v80, s[22:23]
; __device__ __forceinline__ u32x4 pack8(f32x4 a, f32x4 b) { u32x4 w; w.x = cvt_pk_bf16(a[0], a[1]); w.y = cvt_pk_bf16(a[2], a[3]); w.z = cvt_pk_bf16(b[0], b[1]); w.w = cvt_pk_bf16(b[2], b[3]); return w; }
;     __device__ __forceinline__ void operator()(const f32x4 (&acc)[2][2][4][2], const Unit& u, int wr, int wc, int fr, int fq) const {
;     ...
;                 const int row = row0 + ai * HALF + m * 16; const size_t off = (size_t)row * 2048 + col;
;                 float s = 0.f;
; #pragma unroll
;                 for (int bj = 0; bj < 2; ++bj) {
;                     f32x4 b0, b1;
;                     if (BASE_F32) { const float* bp = (const float*)base + off + bj * 32; b0 = *(const f32x4*)bp; b1 = *(const f32x4*)(bp + 4); }
;                     else { const u32x4 w = *(const u32x4*)((const bf16_t*)base + off + bj * 32);
;                         b0 = (f32x4){__uint_as_float(w.x << 16), __uint_as_float(w.x & 0xffff0000u), __uint_as_float(w.y << 16), __uint_as_float(w.y & 0xffff0000u)};
;                         b1 = (f32x4){__uint_as_float(w.z << 16), __uint_as_float(w.z & 0xffff0000u), __uint_as_float(w.w << 16), __uint_as_float(w.w & 0xffff0000u)}; }
;                     const f32x4 h0 = b0 + acc[ai][bj][m][0], h1 = b1 + acc[ai][bj][m][1];
;                     s += (h0[0] * h0[0] + h0[1] * h0[1]) + (h0[2] * h0[2] + h0[3] * h0[3]) + (h1[0] * h1[0] + h1[1] * h1[1]) + (h1[2] * h1[2] + h1[3] * h1[3]);
;                     *(u32x4*)(H + off + bj * 32) = pack8(h0, h1);
;                 }
;                 s += __shfl_xor(s, 16); s += __shfl_xor(s, 32);
;                 if (fq == 0) __hip_atomic_fetch_add(ss + row, s, __ATOMIC_RELAXED, __HIP_MEMORY_SCOPE_AGENT);
.LBB0_337:
	v_or_b32_e32 v80, 48, v136
	s_waitcnt lgkmcnt(0)
	v_ashrrev_i32_e32 v81, 31, v80
	v_lshlrev_b64 v[82:83], 12, v[80:81]
	v_lshl_add_u64 v[82:83], s[6:7], 0, v[82:83]
	v_lshl_add_u64 v[86:87], v[134:135], 1, v[82:83]
	s_nop 1
	s_waitcnt vmcnt(15)
	v_mov_b32_e32 v82, v186
	v_mov_b32_e32 v83, v187
	v_mov_b32_e32 v84, v188
	v_mov_b32_e32 v85, v189
	s_nop 0
	v_lshlrev_b32_e32 v88, 16, v82
	v_and_b32_e32 v89, 0xffff0000, v82
	v_lshlrev_b32_e32 v82, 16, v83
	v_and_b32_e32 v83, 0xffff0000, v83
	v_lshlrev_b32_e32 v90, 16, v84
	v_and_b32_e32 v91, 0xffff0000, v84
	v_lshlrev_b32_e32 v84, 16, v85
	v_and_b32_e32 v85, 0xffff0000, v85
	v_pk_add_f32 v[82:83], v[78:79], v[82:83]
	v_pk_add_f32 v[88:89], v[76:77], v[88:89]
	v_pk_add_f32 v[84:85], v[74:75], v[84:85]
	v_pk_add_f32 v[90:91], v[72:73], v[90:91]
	v_cvt_pk_bf16_f32 v72, v88, v89
	v_cvt_pk_bf16_f32 v73, v82, v83
	v_mul_f32_e32 v89, v89, v89
	v_cvt_pk_bf16_f32 v74, v90, v91
	v_cvt_pk_bf16_f32 v75, v84, v85
	s_nop 1
	s_waitcnt vmcnt(14)
	v_mov_b32_e32 v76, v190
	v_mov_b32_e32 v77, v191
	v_mov_b32_e32 v78, v192
	v_mov_b32_e32 v79, v193
	v_mul_f32_e32 v83, v83, v83
	v_mul_f32_e32 v91, v91, v91
	v_fmac_f32_e32 v89, v88, v88
	v_fmac_f32_e32 v83, v82, v82
	v_mul_f32_e32 v85, v85, v85
	v_fmac_f32_e32 v91, v90, v90
	v_add_f32_e32 v82, v89, v83
	v_fmac_f32_e32 v85, v84, v84
	v_add_f32_e32 v82, v91, v82
	v_add_f32_e32 v88, v85, v82
	global_store_dwordx4 v[86:87], v[72:75], off
	s_nop 0
	v_lshlrev_b32_e32 v82, 16, v76
	v_and_b32_e32 v83, 0xffff0000, v76
	v_lshlrev_b32_e32 v76, 16, v77
	v_and_b32_e32 v77, 0xffff0000, v77
	v_lshlrev_b32_e32 v84, 16, v78
	v_and_b32_e32 v85, 0xffff0000, v78
	v_lshlrev_b32_e32 v78, 16, v79
	v_and_b32_e32 v79, 0xffff0000, v79
	v_pk_add_f32 v[70:71], v[70:71], v[76:77]
	v_pk_add_f32 v[68:69], v[68:69], v[82:83]
	v_pk_add_f32 v[76:77], v[66:67], v[78:79]
	v_pk_add_f32 v[78:79], v[64:65], v[84:85]
	v_mul_f32_e32 v64, v69, v69
	v_mul_f32_e32 v65, v71, v71
	v_mul_f32_e32 v66, v79, v79
	v_fmac_f32_e32 v64, v68, v68
	v_fmac_f32_e32 v65, v70, v70
	v_mul_f32_e32 v67, v77, v77
	v_fmac_f32_e32 v66, v78, v78
	v_add_f32_e32 v64, v64, v65
	v_add_f32_e32 v64, v66, v64
	v_fmac_f32_e32 v67, v76, v76
	v_add_f32_e32 v64, v67, v64
	v_add_f32_e32 v64, v88, v64
	ds_bpermute_b32 v65, v114, v64
	v_cvt_pk_bf16_f32 v66, v68, v69
	v_cvt_pk_bf16_f32 v67, v70, v71
	v_cvt_pk_bf16_f32 v68, v78, v79
	v_cvt_pk_bf16_f32 v69, v76, v77
	s_waitcnt lgkmcnt(0)
	v_add_f32_e32 v64, v64, v65
	ds_bpermute_b32 v65, v115, v64
	global_store_dwordx4 v[86:87], v[66:69], off offset:64
	s_waitcnt lgkmcnt(0)
	v_add_f32_e32 v64, v64, v65
	s_mov_b32 s22, 0
	s_mov_b32 s23, 0xffff0000
	v_cndmask_b32_e64 v229, v229, v64, s[22:23]
	global_atomic_add_f32 v[230:231], v229, off
.LBB0_339:
	v_add_u32_e32 v64, 0x80, v136
	s_waitcnt lgkmcnt(0)
	v_ashrrev_i32_e32 v65, 31, v64
	v_lshlrev_b64 v[66:67], 12, v[64:65]
	v_lshl_add_u64 v[66:67], s[6:7], 0, v[66:67]
	v_lshl_add_u64 v[70:71], v[134:135], 1, v[66:67]
	s_nop 1
	s_waitcnt vmcnt(15)
	v_mov_b32_e32 v66, v194
	v_mov_b32_e32 v67, v195
	v_mov_b32_e32 v68, v196
	v_mov_b32_e32 v69, v197
	s_nop 0
	v_lshlrev_b32_e32 v72, 16, v66
	v_and_b32_e32 v73, 0xffff0000, v66
	v_lshlrev_b32_e32 v66, 16, v67
	v_and_b32_e32 v67, 0xffff0000, v67
	v_lshlrev_b32_e32 v74, 16, v68
	v_and_b32_e32 v75, 0xffff0000, v68
	v_lshlrev_b32_e32 v68, 16, v69
	v_and_b32_e32 v69, 0xffff0000, v69
	v_pk_add_f32 v[66:67], v[62:63], v[66:67]
	v_pk_add_f32 v[72:73], v[60:61], v[72:73]
	v_pk_add_f32 v[68:69], v[58:59], v[68:69]
	v_pk_add_f32 v[74:75], v[56:57], v[74:75]
	v_cvt_pk_bf16_f32 v56, v72, v73
	v_cvt_pk_bf16_f32 v57, v66, v67
	v_mul_f32_e32 v73, v73, v73
	v_cvt_pk_bf16_f32 v58, v74, v75
	v_cvt_pk_bf16_f32 v59, v68, v69
	s_nop 1
	s_waitcnt vmcnt(14)
	v_mov_b32_e32 v60, v198
	v_mov_b32_e32 v61, v199
	v_mov_b32_e32 v62, v200
	v_mov_b32_e32 v63, v201
	v_mul_f32_e32 v67, v67, v67
	v_mul_f32_e32 v75, v75, v75
	v_fmac_f32_e32 v73, v72, v72
	v_fmac_f32_e32 v67, v66, v66
	v_mul_f32_e32 v69, v69, v69
	v_fmac_f32_e32 v75, v74, v74
	v_add_f32_e32 v66, v73, v67
	v_fmac_f32_e32 v69, v68, v68
	v_add_f32_e32 v66, v75, v66
	v_add_f32_e32 v72, v69, v66
	global_store_dwordx4 v[70:71], v[56:59], off
	s_nop 0
	v_lshlrev_b32_e32 v66, 16, v60
	v_and_b32_e32 v67, 0xffff0000, v60
	v_lshlrev_b32_e32 v60, 16, v61
	v_and_b32_e32 v61, 0xffff0000, v61
	v_lshlrev_b32_e32 v68, 16, v62
	v_and_b32_e32 v69, 0xffff0000, v62
	v_lshlrev_b32_e32 v62, 16, v63
	v_and_b32_e32 v63, 0xffff0000, v63
	v_pk_add_f32 v[54:55], v[54:55], v[60:61]
	v_pk_add_f32 v[52:53], v[52:53], v[66:67]
	v_pk_add_f32 v[60:61], v[50:51], v[62:63]
	v_pk_add_f32 v[62:63], v[48:49], v[68:69]
	v_mul_f32_e32 v48, v53, v53
	v_mul_f32_e32 v49, v55, v55
	v_mul_f32_e32 v50, v63, v63
	v_fmac_f32_e32 v48, v52, v52
	v_fmac_f32_e32 v49, v54, v54
	v_mul_f32_e32 v51, v61, v61
	v_fmac_f32_e32 v50, v62, v62
	v_add_f32_e32 v48, v48, v49
	v_add_f32_e32 v48, v50, v48
	v_fmac_f32_e32 v51, v60, v60
	v_add_f32_e32 v48, v51, v48
	v_add_f32_e32 v48, v72, v48
	ds_bpermute_b32 v49, v114, v48
	v_cvt_pk_bf16_f32 v50, v52, v53
	v_cvt_pk_bf16_f32 v51, v54, v55
	v_cvt_pk_bf16_f32 v52, v62, v63
	v_cvt_pk_bf16_f32 v53, v60, v61
	s_waitcnt lgkmcnt(0)
	v_add_f32_e32 v48, v48, v49
	ds_bpermute_b32 v49, v115, v48
	global_store_dwordx4 v[70:71], v[50:53], off offset:64
	s_waitcnt lgkmcnt(0)
	v_add_f32_e32 v48, v48, v49
	v_mov_b32_e32 v229, v48
; __device__ __forceinline__ u32x4 pack8(f32x4 a, f32x4 b) { u32x4 w; w.x = cvt_pk_bf16(a[0], a[1]); w.y = cvt_pk_bf16(a[2], a[3]); w.z = cvt_pk_bf16(b[0], b[1]); w.w = cvt_pk_bf16(b[2], b[3]); return w; }
;     __device__ __forceinline__ void operator()(const f32x4 (&acc)[2][2][4][2], const Unit& u, int wr, int wc, int fr, int fq) const {
;     ...
;                 const int row = row0 + ai * HALF + m * 16; const size_t off = (size_t)row * 2048 + col;
;                 float s = 0.f;
; #pragma unroll
;                 for (int bj = 0; bj < 2; ++bj) {
;                     f32x4 b0, b1;
;                     if (BASE_F32) { const float* bp = (const float*)base + off + bj * 32; b0 = *(const f32x4*)bp; b1 = *(const f32x4*)(bp + 4); }
;                     else { const u32x4 w = *(const u32x4*)((const bf16_t*)base + off + bj * 32);
;                         b0 = (f32x4){__uint_as_float(w.x << 16), __uint_as_float(w.x & 0xffff0000u), __uint_as_float(w.y << 16), __uint_as_float(w.y & 0xffff0000u)};
;                         b1 = (f32x4){__uint_as_float(w.z << 16), __uint_as_float(w.z & 0xffff0000u), __uint_as_float(w.w << 16), __uint_as_float(w.w & 0xffff0000u)}; }
;                     const f32x4 h0 = b0 + acc[ai][bj][m][0], h1 = b1 + acc[ai][bj][m][1];
;                     s += (h0[0] * h0[0] + h0[1] * h0[1]) + (h0[2] * h0[2] + h0[3] * h0[3]) + (h1[0] * h1[0] + h1[1] * h1[1]) + (h1[2] * h1[2] + h1[3] * h1[3]);
;                     *(u32x4*)(H + off + bj * 32) = pack8(h0, h1);
;                 }
;                 s += __shfl_xor(s, 16); s += __shfl_xor(s, 32);
;                 if (fq == 0) __hip_atomic_fetch_add(ss + row, s, __ATOMIC_RELAXED, __HIP_MEMORY_SCOPE_AGENT);
.LBB0_341:
	v_add_u32_e32 v48, 0x90, v136
	s_waitcnt lgkmcnt(0)
	v_ashrrev_i32_e32 v49, 31, v48
	v_lshlrev_b64 v[50:51], 12, v[48:49]
	v_lshl_add_u64 v[50:51], s[6:7], 0, v[50:51]
	v_lshl_add_u64 v[54:55], v[134:135], 1, v[50:51]
	s_nop 1
	s_waitcnt vmcnt(15)
	v_mov_b32_e32 v50, v212
	v_mov_b32_e32 v51, v213
	v_mov_b32_e32 v52, v214
	v_mov_b32_e32 v53, v215
	s_nop 0
	v_lshlrev_b32_e32 v56, 16, v50
	v_and_b32_e32 v57, 0xffff0000, v50
	v_lshlrev_b32_e32 v50, 16, v51
	v_and_b32_e32 v51, 0xffff0000, v51
	v_lshlrev_b32_e32 v58, 16, v52
	v_and_b32_e32 v59, 0xffff0000, v52
	v_lshlrev_b32_e32 v52, 16, v53
	v_and_b32_e32 v53, 0xffff0000, v53
	v_pk_add_f32 v[50:51], v[46:47], v[50:51]
	v_pk_add_f32 v[56:57], v[44:45], v[56:57]
	v_pk_add_f32 v[52:53], v[42:43], v[52:53]
	v_pk_add_f32 v[58:59], v[40:41], v[58:59]
	v_cvt_pk_bf16_f32 v40, v56, v57
	v_cvt_pk_bf16_f32 v41, v50, v51
	v_mul_f32_e32 v57, v57, v57
	v_cvt_pk_bf16_f32 v42, v58, v59
	v_cvt_pk_bf16_f32 v43, v52, v53
	s_nop 1
	s_waitcnt vmcnt(14)
	v_mov_b32_e32 v44, v216
	v_mov_b32_e32 v45, v217
	v_mov_b32_e32 v46, v218
	v_mov_b32_e32 v47, v219
	v_mul_f32_e32 v51, v51, v51
	v_mul_f32_e32 v59, v59, v59
	v_fmac_f32_e32 v57, v56, v56
	v_fmac_f32_e32 v51, v50, v50
	v_mul_f32_e32 v53, v53, v53
	v_fmac_f32_e32 v59, v58, v58
	v_add_f32_e32 v50, v57, v51
	v_fmac_f32_e32 v53, v52, v52
	v_add_f32_e32 v50, v59, v50
	v_add_f32_e32 v56, v53, v50
	global_store_dwordx4 v[54:55], v[40:43], off
	s_nop 0
	v_lshlrev_b32_e32 v50, 16, v44
	v_and_b32_e32 v51, 0xffff0000, v44
	v_lshlrev_b32_e32 v44, 16, v45
	v_and_b32_e32 v45, 0xffff0000, v45
	v_lshlrev_b32_e32 v52, 16, v46
	v_and_b32_e32 v53, 0xffff0000, v46
	v_lshlrev_b32_e32 v46, 16, v47
	v_and_b32_e32 v47, 0xffff0000, v47
	v_pk_add_f32 v[38:39], v[38:39], v[44:45]
	v_pk_add_f32 v[36:37], v[36:37], v[50:51]
	v_pk_add_f32 v[44:45], v[34:35], v[46:47]
	v_pk_add_f32 v[46:47], v[32:33], v[52:53]
	v_mul_f32_e32 v32, v37, v37
	v_mul_f32_e32 v33, v39, v39
	v_mul_f32_e32 v34, v47, v47
	v_fmac_f32_e32 v32, v36, v36
	v_fmac_f32_e32 v33, v38, v38
	v_mul_f32_e32 v35, v45, v45
	v_fmac_f32_e32 v34, v46, v46
	v_add_f32_e32 v32, v32, v33
	v_add_f32_e32 v32, v34, v32
	v_fmac_f32_e32 v35, v44, v44
	v_add_f32_e32 v32, v35, v32
	v_add_f32_e32 v32, v56, v32
	ds_bpermute_b32 v33, v114, v32
	v_cvt_pk_bf16_f32 v34, v36, v37
	v_cvt_pk_bf16_f32 v35, v38, v39
	v_cvt_pk_bf16_f32 v36, v46, v47
	v_cvt_pk_bf16_f32 v37, v44, v45
	s_waitcnt lgkmcnt(0)
	v_add_f32_e32 v32, v32, v33
	ds_bpermute_b32 v33, v115, v32
	global_store_dwordx4 v[54:55], v[34:37], off offset:64
	s_waitcnt lgkmcnt(0)
	v_add_f32_e32 v32, v32, v33
	s_mov_b32 s22, 0xffff0000
	s_mov_b32 s23, 0
	v_cndmask_b32_e64 v229, v229, v32, s[22:23]
.LBB0_343:
	v_add_u32_e32 v32, 0xa0, v136
	s_waitcnt lgkmcnt(0)
	v_ashrrev_i32_e32 v33, 31, v32
	v_lshlrev_b64 v[34:35], 12, v[32:33]
	v_lshl_add_u64 v[34:35], s[6:7], 0, v[34:35]
	v_lshl_add_u64 v[38:39], v[134:135], 1, v[34:35]
	s_nop 1
	s_waitcnt vmcnt(14)
	v_mov_b32_e32 v34, v152
	v_mov_b32_e32 v35, v153
	v_mov_b32_e32 v36, v154
	v_mov_b32_e32 v37, v155
	s_nop 0
	v_lshlrev_b32_e32 v40, 16, v34
	v_and_b32_e32 v41, 0xffff0000, v34
	v_lshlrev_b32_e32 v34, 16, v35
	v_and_b32_e32 v35, 0xffff0000, v35
	v_lshlrev_b32_e32 v42, 16, v36
	v_and_b32_e32 v43, 0xffff0000, v36
	v_lshlrev_b32_e32 v36, 16, v37
	v_and_b32_e32 v37, 0xffff0000, v37
	v_pk_add_f32 v[34:35], v[30:31], v[34:35]
	v_pk_add_f32 v[40:41], v[28:29], v[40:41]
	v_pk_add_f32 v[36:37], v[26:27], v[36:37]
	v_pk_add_f32 v[42:43], v[24:25], v[42:43]
	v_cvt_pk_bf16_f32 v24, v40, v41
	v_cvt_pk_bf16_f32 v25, v34, v35
	v_mul_f32_e32 v41, v41, v41
	v_cvt_pk_bf16_f32 v26, v42, v43
	v_cvt_pk_bf16_f32 v27, v36, v37
	s_nop 1
	s_waitcnt vmcnt(13)
	v_mov_b32_e32 v28, v156
	v_mov_b32_e32 v29, v157
	v_mov_b32_e32 v30, v158
	v_mov_b32_e32 v31, v159
	v_mul_f32_e32 v35, v35, v35
	v_mul_f32_e32 v43, v43, v43
	v_fmac_f32_e32 v41, v40, v40
	v_fmac_f32_e32 v35, v34, v34
	v_mul_f32_e32 v37, v37, v37
	v_fmac_f32_e32 v43, v42, v42
	v_add_f32_e32 v34, v41, v35
	v_fmac_f32_e32 v37, v36, v36
	v_add_f32_e32 v34, v43, v34
	v_add_f32_e32 v40, v37, v34
	global_store_dwordx4 v[38:39], v[24:27], off
	s_nop 0
	v_lshlrev_b32_e32 v34, 16, v28
	v_and_b32_e32 v35, 0xffff0000, v28
	v_lshlrev_b32_e32 v28, 16, v29
	v_and_b32_e32 v29, 0xffff0000, v29
	v_lshlrev_b32_e32 v36, 16, v30
	v_and_b32_e32 v37, 0xffff0000, v30
	v_lshlrev_b32_e32 v30, 16, v31
	v_and_b32_e32 v31, 0xffff0000, v31
	v_pk_add_f32 v[22:23], v[22:23], v[28:29]
	v_pk_add_f32 v[20:21], v[20:21], v[34:35]
	v_pk_add_f32 v[28:29], v[18:19], v[30:31]
	v_pk_add_f32 v[30:31], v[16:17], v[36:37]
	v_mul_f32_e32 v16, v21, v21
	v_mul_f32_e32 v17, v23, v23
	v_mul_f32_e32 v18, v31, v31
	v_fmac_f32_e32 v16, v20, v20
	v_fmac_f32_e32 v17, v22, v22
	v_mul_f32_e32 v19, v29, v29
	v_fmac_f32_e32 v18, v30, v30
	v_add_f32_e32 v16, v16, v17
	v_add_f32_e32 v16, v18, v16
	v_fmac_f32_e32 v19, v28, v28
	v_add_f32_e32 v16, v19, v16
	v_add_f32_e32 v16, v40, v16
	ds_bpermute_b32 v17, v114, v16
	v_cvt_pk_bf16_f32 v18, v20, v21
	v_cvt_pk_bf16_f32 v19, v22, v23
	v_cvt_pk_bf16_f32 v20, v30, v31
	v_cvt_pk_bf16_f32 v21, v28, v29
	s_waitcnt lgkmcnt(0)
	v_add_f32_e32 v16, v16, v17
	ds_bpermute_b32 v17, v115, v16
	global_store_dwordx4 v[38:39], v[18:21], off offset:64
	s_waitcnt lgkmcnt(0)
	v_add_f32_e32 v16, v16, v17
	s_mov_b32 s22, 0
	s_mov_b32 s23, 0xffff
	v_cndmask_b32_e64 v229, v229, v16, s[22:23]
; #define PG8_BAR __builtin_amdgcn_s_barrier()
; template <class Epi, class Sched, bool ALIGN_EPI = false, bool SP2 = false>
; __device__ __forceinline__ void gemm_phase(PG8_LAS unsigned char* lds, const Gemm g, const Sched& S, const Epi& E) {
;     ...
;         if (!has_next) break;
; #pragma unroll
;         for (int a = 0; a < 2; ++a)
; #pragma unroll
;             for (int b = 0; b < 2; ++b)
; #pragma unroll
;                 for (int m = 0; m < 4; ++m)
; #pragma unroll
;                     for (int n = 0; n < 2; ++n) acc[a][b][m][n] = (f32x4){0.f, 0.f, 0.f, 0.f};
;         cur = nxt; cA = nA; cB = nB; st = nst; ++ui;
;         if constexpr (ALIGN_EPI) { if (wr == 1) PG8_BAR; }
;     __device__ __forceinline__ void operator()(const f32x4 (&acc)[2][2][4][2], const Unit& u, int wr, int wc, int fr, int fq) const {
;     ...
;                 const int row = row0 + ai * HALF + m * 16; const size_t off = (size_t)row * 2048 + col;
;                 float s = 0.f;
; #pragma unroll
;                 for (int bj = 0; bj < 2; ++bj) {
;                     f32x4 b0, b1;
;                     if (BASE_F32) { const float* bp = (const float*)base + off + bj * 32; b0 = *(const f32x4*)bp; b1 = *(const f32x4*)(bp + 4); }
;                     else { const u32x4 w = *(const u32x4*)((const bf16_t*)base + off + bj * 32);
;                         b0 = (f32x4){__uint_as_float(w.x << 16), __uint_as_float(w.x & 0xffff0000u), __uint_as_float(w.y << 16), __uint_as_float(w.y & 0xffff0000u)};
;                         b1 = (f32x4){__uint_as_float(w.z << 16), __uint_as_float(w.z & 0xffff0000u), __uint_as_float(w.w << 16), __uint_as_float(w.w & 0xffff0000u)}; }
;                     const f32x4 h0 = b0 + acc[ai][bj][m][0], h1 = b1 + acc[ai][bj][m][1];
;                     s += (h0[0] * h0[0] + h0[1] * h0[1]) + (h0[2] * h0[2] + h0[3] * h0[3]) + (h1[0] * h1[0] + h1[1] * h1[1]) + (h1[2] * h1[2] + h1[3] * h1[3]);
;                     *(u32x4*)(H + off + bj * 32) = pack8(h0, h1);
;                 }
;                 s += __shfl_xor(s, 16); s += __shfl_xor(s, 32);
;                 if (fq == 0) __hip_atomic_fetch_add(ss + row, s, __ATOMIC_RELAXED, __HIP_MEMORY_SCOPE_AGENT);
;                 if (m & 1) asm volatile("" ::: "memory");
;             }
.LBB0_345:
	v_add_u32_e32 v16, 0xb0, v136
	s_waitcnt lgkmcnt(0)
	v_ashrrev_i32_e32 v17, 31, v16
	v_lshlrev_b64 v[18:19], 12, v[16:17]
	v_lshl_add_u64 v[18:19], s[6:7], 0, v[18:19]
	v_lshl_add_u64 v[22:23], v[134:135], 1, v[18:19]
	s_nop 1
	s_waitcnt vmcnt(13)
	v_mov_b32_e32 v18, v160
	v_mov_b32_e32 v19, v161
	v_mov_b32_e32 v20, v162
	v_mov_b32_e32 v21, v163
	s_nop 0
	v_lshlrev_b32_e32 v24, 16, v18
	v_and_b32_e32 v25, 0xffff0000, v18
	v_lshlrev_b32_e32 v18, 16, v19
	v_and_b32_e32 v19, 0xffff0000, v19
	v_lshlrev_b32_e32 v26, 16, v20
	v_and_b32_e32 v27, 0xffff0000, v20
	v_lshlrev_b32_e32 v20, 16, v21
	v_and_b32_e32 v21, 0xffff0000, v21
	v_pk_add_f32 v[18:19], v[14:15], v[18:19]
	v_pk_add_f32 v[24:25], v[12:13], v[24:25]
	v_pk_add_f32 v[20:21], v[10:11], v[20:21]
	v_pk_add_f32 v[26:27], v[8:9], v[26:27]
	v_cvt_pk_bf16_f32 v8, v24, v25
	v_cvt_pk_bf16_f32 v9, v18, v19
	v_mul_f32_e32 v25, v25, v25
	v_cvt_pk_bf16_f32 v10, v26, v27
	v_cvt_pk_bf16_f32 v11, v20, v21
	s_nop 1
	s_waitcnt vmcnt(12)
	v_mov_b32_e32 v12, v164
	v_mov_b32_e32 v13, v165
	v_mov_b32_e32 v14, v166
	v_mov_b32_e32 v15, v167
	v_mul_f32_e32 v19, v19, v19
	v_mul_f32_e32 v27, v27, v27
	v_fmac_f32_e32 v25, v24, v24
	v_fmac_f32_e32 v19, v18, v18
	v_mul_f32_e32 v21, v21, v21
	v_fmac_f32_e32 v27, v26, v26
	v_add_f32_e32 v18, v25, v19
	v_fmac_f32_e32 v21, v20, v20
	v_add_f32_e32 v18, v27, v18
	v_add_f32_e32 v24, v21, v18
	global_store_dwordx4 v[22:23], v[8:11], off
	s_nop 0
	v_lshlrev_b32_e32 v18, 16, v12
	v_and_b32_e32 v19, 0xffff0000, v12
	v_lshlrev_b32_e32 v12, 16, v13
	v_and_b32_e32 v13, 0xffff0000, v13
	v_lshlrev_b32_e32 v20, 16, v14
	v_and_b32_e32 v21, 0xffff0000, v14
	v_lshlrev_b32_e32 v14, 16, v15
	v_and_b32_e32 v15, 0xffff0000, v15
	v_pk_add_f32 v[6:7], v[6:7], v[12:13]
	v_pk_add_f32 v[4:5], v[4:5], v[18:19]
	v_pk_add_f32 v[12:13], v[2:3], v[14:15]
	v_pk_add_f32 v[14:15], v[0:1], v[20:21]
	v_mul_f32_e32 v0, v5, v5
	v_mul_f32_e32 v1, v7, v7
	v_mul_f32_e32 v2, v15, v15
	v_fmac_f32_e32 v0, v4, v4
	v_fmac_f32_e32 v1, v6, v6
	v_mul_f32_e32 v3, v13, v13
	v_fmac_f32_e32 v2, v14, v14
	v_add_f32_e32 v0, v0, v1
	v_add_f32_e32 v0, v2, v0
	v_fmac_f32_e32 v3, v12, v12
	v_add_f32_e32 v0, v3, v0
	v_add_f32_e32 v0, v24, v0
	ds_bpermute_b32 v1, v114, v0
	v_cvt_pk_bf16_f32 v2, v4, v5
	v_cvt_pk_bf16_f32 v3, v6, v7
	v_cvt_pk_bf16_f32 v4, v14, v15
	v_cvt_pk_bf16_f32 v5, v12, v13
	s_waitcnt lgkmcnt(0)
	v_add_f32_e32 v0, v0, v1
	ds_bpermute_b32 v1, v115, v0
	global_store_dwordx4 v[22:23], v[2:5], off offset:64
	s_waitcnt lgkmcnt(0)
	v_add_f32_e32 v0, v0, v1
	s_mov_b32 s22, 0
	s_mov_b32 s23, 0xffff0000
	v_cndmask_b32_e64 v229, v229, v0, s[22:23]
	global_atomic_add_f32 v[230:231], v229, off offset:512
.LBB0_347:
	s_andn2_b64 vcc, exec, s[4:5]
	s_mov_b64 s[4:5], -1
	s_cbranch_vccnz .LBB0_316
	s_andn2_b64 vcc, exec, s[0:1]
	s_cbranch_vccnz .LBB0_315
	s_barrier
	s_branch .LBB0_315

; __device__ __forceinline__ u32x4 pack8(f32x4 a, f32x4 b) { u32x4 w; w.x = cvt_pk_bf16(a[0], a[1]); w.y = cvt_pk_bf16(a[2], a[3]); w.z = cvt_pk_bf16(b[0], b[1]); w.w = cvt_pk_bf16(b[2], b[3]); return w; }
;     __device__ __forceinline__ void operator()(const f32x4 (&acc)[2][2][4][2], const Unit& u, int wr, int wc, int fr, int fq) const {
;         const int row0 = u.pm * BM + wr * 64 + fr, col = u.pn * BM + wc * 64 + 8 * fq;
; #pragma unroll
;         for (int ai = 0; ai < 2; ++ai)
; #pragma unroll
;             for (int m = 0; m < 4; ++m) {
;                 const int row = row0 + ai * HALF + m * 16; const size_t off = (size_t)row * 2048 + col;
;                 float s = 0.f;
; #pragma unroll
;                 for (int bj = 0; bj < 2; ++bj) {
;                     f32x4 b0, b1;
;                     if (BASE_F32) { const float* bp = (const float*)base + off + bj * 32; b0 = *(const f32x4*)bp; b1 = *(const f32x4*)(bp + 4); }
;                     else { const u32x4 w = *(const u32x4*)((const bf16_t*)base + off + bj * 32);
;                         b0 = (f32x4){__uint_as_float(w.x << 16), __uint_as_float(w.x & 0xffff0000u), __uint_as_float(w.y << 16), __uint_as_float(w.y & 0xffff0000u)};
;                         b1 = (f32x4){__uint_as_float(w.z << 16), __uint_as_float(w.z & 0xffff0000u), __uint_as_float(w.w << 16), __uint_as_float(w.w & 0xffff0000u)}; }
;                     const f32x4 h0 = b0 + acc[ai][bj][m][0], h1 = b1 + acc[ai][bj][m][1];
;                     s += (h0[0] * h0[0] + h0[1] * h0[1]) + (h0[2] * h0[2] + h0[3] * h0[3]) + (h1[0] * h1[0] + h1[1] * h1[1]) + (h1[2] * h1[2] + h1[3] * h1[3]);
;                     *(u32x4*)(H + off + bj * 32) = pack8(h0, h1);
;                 }
;                 s += __shfl_xor(s, 16); s += __shfl_xor(s, 32);
.LBB0_620:
	v_lshl_add_u32 v136, s26, 8, v139
	v_ashrrev_i32_e32 v137, 31, v136
	v_lshl_or_b32 v134, s28, 8, v141
	v_lshlrev_b64 v[144:145], 12, v[136:137]
	v_ashrrev_i32_e32 v135, 31, v134
	v_lshl_add_u64 v[144:145], s[10:11], 0, v[144:145]
	v_lshl_add_u64 v[148:149], v[134:135], 1, v[144:145]
	v_mov_b32_e32 v170, v136
	v_ashrrev_i32_e32 v171, 31, v170
	v_lshlrev_b64 v[170:171], 12, v[170:171]
	v_lshl_add_u64 v[170:171], s[10:11], 0, v[170:171]
	v_lshl_add_u64 v[170:171], v[134:135], 1, v[170:171]
	global_load_dwordx4 v[154:157], v[170:171], off
	global_load_dwordx4 v[158:161], v[170:171], off offset:64
	v_add_u32_e32 v170, 0x10, v136
	v_ashrrev_i32_e32 v171, 31, v170
	v_lshlrev_b64 v[170:171], 12, v[170:171]
	v_lshl_add_u64 v[170:171], s[10:11], 0, v[170:171]
	v_lshl_add_u64 v[170:171], v[134:135], 1, v[170:171]
	global_load_dwordx4 v[162:165], v[170:171], off
	global_load_dwordx4 v[166:169], v[170:171], off offset:64
	v_add_u32_e32 v170, 0x20, v136
	v_ashrrev_i32_e32 v171, 31, v170
	v_lshlrev_b64 v[170:171], 12, v[170:171]
	v_lshl_add_u64 v[170:171], s[10:11], 0, v[170:171]
	v_lshl_add_u64 v[170:171], v[134:135], 1, v[170:171]
	global_load_dwordx4 v[182:185], v[170:171], off
	global_load_dwordx4 v[186:189], v[170:171], off offset:64
	v_add_u32_e32 v170, 0x30, v136
	v_ashrrev_i32_e32 v171, 31, v170
	v_lshlrev_b64 v[170:171], 12, v[170:171]
	v_lshl_add_u64 v[170:171], s[10:11], 0, v[170:171]
	v_lshl_add_u64 v[170:171], v[134:135], 1, v[170:171]
	global_load_dwordx4 v[190:193], v[170:171], off
	global_load_dwordx4 v[194:197], v[170:171], off offset:64
	v_add_u32_e32 v170, 0x80, v136
	v_ashrrev_i32_e32 v171, 31, v170
	v_lshlrev_b64 v[170:171], 12, v[170:171]
	v_lshl_add_u64 v[170:171], s[10:11], 0, v[170:171]
	v_lshl_add_u64 v[170:171], v[134:135], 1, v[170:171]
	global_load_dwordx4 v[198:201], v[170:171], off
	global_load_dwordx4 v[212:215], v[170:171], off offset:64
	v_add_u32_e32 v170, 0x90, v136
	v_ashrrev_i32_e32 v171, 31, v170
	v_lshlrev_b64 v[170:171], 12, v[170:171]
	v_lshl_add_u64 v[170:171], s[10:11], 0, v[170:171]
	v_lshl_add_u64 v[170:171], v[134:135], 1, v[170:171]
	global_load_dwordx4 v[216:219], v[170:171], off
	global_load_dwordx4 v[220:223], v[170:171], off offset:64
	v_and_b32_e32 v230, 48, v209
	v_add_u32_e32 v230, v230, v136
	v_mov_b32_e32 v231, 0
	v_lshl_add_u64 v[230:231], v[230:231], 2, s[12:13]
	s_nop 1
	s_waitcnt vmcnt(11)
	v_mov_b32_e32 v144, v154
	v_mov_b32_e32 v145, v155
	v_mov_b32_e32 v146, v156
	v_mov_b32_e32 v147, v157
	s_nop 0
	v_lshlrev_b32_e32 v150, 16, v144
	v_and_b32_e32 v151, 0xffff0000, v144
	v_lshlrev_b32_e32 v144, 16, v145
	v_and_b32_e32 v145, 0xffff0000, v145
	v_lshlrev_b32_e32 v152, 16, v146
	v_and_b32_e32 v153, 0xffff0000, v146
	v_lshlrev_b32_e32 v146, 16, v147
	v_and_b32_e32 v147, 0xffff0000, v147
	v_pk_add_f32 v[126:127], v[126:127], v[144:145]
	v_pk_add_f32 v[124:125], v[124:125], v[150:151]
	v_pk_add_f32 v[144:145], v[122:123], v[146:147]
	v_pk_add_f32 v[122:123], v[120:121], v[152:153]
	v_mul_f32_e32 v120, v125, v125
	v_mul_f32_e32 v121, v127, v127
	v_fmac_f32_e32 v120, v124, v124
	v_fmac_f32_e32 v121, v126, v126
	v_add_f32_e32 v120, v120, v121
	v_mul_f32_e32 v121, v123, v123
	v_fmac_f32_e32 v121, v122, v122
	v_add_f32_e32 v120, v121, v120
	v_mul_f32_e32 v121, v145, v145
	v_fmac_f32_e32 v121, v144, v144
	v_add_f32_e32 v143, v121, v120
	v_cvt_pk_bf16_f32 v120, v124, v125
	v_cvt_pk_bf16_f32 v121, v126, v127
	v_cvt_pk_bf16_f32 v122, v122, v123
	v_cvt_pk_bf16_f32 v123, v144, v145
	global_store_dwordx4 v[148:149], v[120:123], off
	s_nop 1
	s_waitcnt vmcnt(11)
	v_mov_b32_e32 v120, v158
	v_mov_b32_e32 v121, v159
	v_mov_b32_e32 v122, v160
	v_mov_b32_e32 v123, v161
	v_add_u32_e32 v170, 0xa0, v136
	v_ashrrev_i32_e32 v171, 31, v170
	v_lshlrev_b64 v[170:171], 12, v[170:171]
	v_lshl_add_u64 v[170:171], s[10:11], 0, v[170:171]
	v_lshl_add_u64 v[170:171], v[134:135], 1, v[170:171]
	global_load_dwordx4 v[154:157], v[170:171], off
	global_load_dwordx4 v[158:161], v[170:171], off offset:64
	s_nop 0
	v_lshlrev_b32_e32 v124, 16, v120
	v_and_b32_e32 v125, 0xffff0000, v120
	v_lshlrev_b32_e32 v120, 16, v121
	v_and_b32_e32 v121, 0xffff0000, v121
	v_lshlrev_b32_e32 v126, 16, v122
	v_and_b32_e32 v127, 0xffff0000, v122
	v_lshlrev_b32_e32 v122, 16, v123
	v_and_b32_e32 v123, 0xffff0000, v123
	v_pk_add_f32 v[118:119], v[118:119], v[120:121]
	v_pk_add_f32 v[116:117], v[116:117], v[124:125]
	v_pk_add_f32 v[120:121], v[114:115], v[122:123]
	v_pk_add_f32 v[114:115], v[112:113], v[126:127]
	v_mul_f32_e32 v112, v117, v117
	v_mul_f32_e32 v113, v119, v119
	v_fmac_f32_e32 v112, v116, v116
	v_fmac_f32_e32 v113, v118, v118
	v_add_f32_e32 v112, v112, v113
	v_mul_f32_e32 v113, v115, v115
	v_fmac_f32_e32 v113, v114, v114
	v_add_f32_e32 v112, v113, v112
	v_mul_f32_e32 v113, v121, v121
	v_fmac_f32_e32 v113, v120, v120
	v_add_f32_e32 v112, v113, v112
	v_add_f32_e32 v122, v143, v112
	v_cvt_pk_bf16_f32 v112, v116, v117
	v_cvt_pk_bf16_f32 v113, v118, v119
	v_cvt_pk_bf16_f32 v114, v114, v115
	v_cvt_pk_bf16_f32 v115, v120, v121
	global_store_dwordx4 v[148:149], v[112:115], off offset:64
	s_nop 1
	v_and_b32_e32 v113, 64, v209
	v_xor_b32_e32 v112, 16, v209
	v_add_u32_e32 v113, 64, v113
	v_cmp_lt_i32_e32 vcc, v112, v113
	v_xor_b32_e32 v115, 32, v209
	s_nop 0
	v_cndmask_b32_e32 v112, v209, v112, vcc
	v_lshlrev_b32_e32 v114, 2, v112
	ds_bpermute_b32 v112, v114, v122
	v_cmp_lt_i32_e32 vcc, v115, v113
	s_waitcnt lgkmcnt(0)
	v_add_f32_e32 v112, v122, v112
	v_cndmask_b32_e32 v113, v209, v115, vcc
	v_lshlrev_b32_e32 v115, 2, v113
	ds_bpermute_b32 v113, v115, v112
	s_waitcnt lgkmcnt(0)
	v_add_f32_e32 v112, v112, v113
	v_mov_b32_e32 v229, v112
; __device__ __forceinline__ u32x4 pack8(f32x4 a, f32x4 b) { u32x4 w; w.x = cvt_pk_bf16(a[0], a[1]); w.y = cvt_pk_bf16(a[2], a[3]); w.z = cvt_pk_bf16(b[0], b[1]); w.w = cvt_pk_bf16(b[2], b[3]); return w; }
;     __device__ __forceinline__ void operator()(const f32x4 (&acc)[2][2][4][2], const Unit& u, int wr, int wc, int fr, int fq) const {
;     ...
;                 const int row = row0 + ai * HALF + m * 16; const size_t off = (size_t)row * 2048 + col;
;                 float s = 0.f;
; #pragma unroll
;                 for (int bj = 0; bj < 2; ++bj) {
;                     f32x4 b0, b1;
;                     if (BASE_F32) { const float* bp = (const float*)base + off + bj * 32; b0 = *(const f32x4*)bp; b1 = *(const f32x4*)(bp + 4); }
;                     else { const u32x4 w = *(const u32x4*)((const bf16_t*)base + off + bj * 32);
;                         b0 = (f32x4){__uint_as_float(w.x << 16), __uint_as_float(w.x & 0xffff0000u), __uint_as_float(w.y << 16), __uint_as_float(w.y & 0xffff0000u)};
;                         b1 = (f32x4){__uint_as_float(w.z << 16), __uint_as_float(w.z & 0xffff0000u), __uint_as_float(w.w << 16), __uint_as_float(w.w & 0xffff0000u)}; }
;                     const f32x4 h0 = b0 + acc[ai][bj][m][0], h1 = b1 + acc[ai][bj][m][1];
;                     s += (h0[0] * h0[0] + h0[1] * h0[1]) + (h0[2] * h0[2] + h0[3] * h0[3]) + (h1[0] * h1[0] + h1[1] * h1[1]) + (h1[2] * h1[2] + h1[3] * h1[3]);
;                     *(u32x4*)(H + off + bj * 32) = pack8(h0, h1);
;                 }
;                 s += __shfl_xor(s, 16); s += __shfl_xor(s, 32);
;                 if (fq == 0) __hip_atomic_fetch_add(ss + row, s, __ATOMIC_RELAXED, __HIP_MEMORY_SCOPE_AGENT);
.LBB0_622:
	v_or_b32_e32 v112, 16, v136
	s_waitcnt lgkmcnt(0)
	v_ashrrev_i32_e32 v113, 31, v112
	v_lshlrev_b64 v[116:117], 12, v[112:113]
	v_lshl_add_u64 v[116:117], s[10:11], 0, v[116:117]
	v_lshl_add_u64 v[120:121], v[134:135], 1, v[116:117]
	s_nop 1
	s_waitcnt vmcnt(13)
	v_mov_b32_e32 v116, v162
	v_mov_b32_e32 v117, v163
	v_mov_b32_e32 v118, v164
	v_mov_b32_e32 v119, v165
	s_nop 0
	v_lshlrev_b32_e32 v122, 16, v116
	v_and_b32_e32 v123, 0xffff0000, v116
	v_lshlrev_b32_e32 v116, 16, v117
	v_and_b32_e32 v117, 0xffff0000, v117
	v_lshlrev_b32_e32 v124, 16, v118
	v_and_b32_e32 v125, 0xffff0000, v118
	v_lshlrev_b32_e32 v118, 16, v119
	v_and_b32_e32 v119, 0xffff0000, v119
	v_pk_add_f32 v[116:117], v[110:111], v[116:117]
	v_pk_add_f32 v[122:123], v[108:109], v[122:123]
	v_pk_add_f32 v[118:119], v[106:107], v[118:119]
	v_pk_add_f32 v[124:125], v[104:105], v[124:125]
	v_cvt_pk_bf16_f32 v104, v122, v123
	v_cvt_pk_bf16_f32 v105, v116, v117
	v_mul_f32_e32 v123, v123, v123
	v_cvt_pk_bf16_f32 v106, v124, v125
	v_cvt_pk_bf16_f32 v107, v118, v119
	s_nop 1
	s_waitcnt vmcnt(12)
	v_mov_b32_e32 v108, v166
	v_mov_b32_e32 v109, v167
	v_mov_b32_e32 v110, v168
	v_mov_b32_e32 v111, v169
	v_add_u32_e32 v170, 0xb0, v136
	v_ashrrev_i32_e32 v171, 31, v170
	v_lshlrev_b64 v[170:171], 12, v[170:171]
	v_lshl_add_u64 v[170:171], s[10:11], 0, v[170:171]
	v_lshl_add_u64 v[170:171], v[134:135], 1, v[170:171]
	global_load_dwordx4 v[162:165], v[170:171], off
	global_load_dwordx4 v[166:169], v[170:171], off offset:64
	v_mul_f32_e32 v117, v117, v117
	v_mul_f32_e32 v125, v125, v125
	v_fmac_f32_e32 v123, v122, v122
	v_fmac_f32_e32 v117, v116, v116
	v_mul_f32_e32 v119, v119, v119
	v_fmac_f32_e32 v125, v124, v124
	v_add_f32_e32 v116, v123, v117
	v_fmac_f32_e32 v119, v118, v118
	v_add_f32_e32 v116, v125, v116
	v_add_f32_e32 v122, v119, v116
	global_store_dwordx4 v[120:121], v[104:107], off
	s_nop 0
	v_lshlrev_b32_e32 v116, 16, v108
	v_and_b32_e32 v117, 0xffff0000, v108
	v_lshlrev_b32_e32 v108, 16, v109
	v_and_b32_e32 v109, 0xffff0000, v109
	v_lshlrev_b32_e32 v118, 16, v110
	v_and_b32_e32 v119, 0xffff0000, v110
	v_lshlrev_b32_e32 v110, 16, v111
	v_and_b32_e32 v111, 0xffff0000, v111
	v_pk_add_f32 v[102:103], v[102:103], v[108:109]
	v_pk_add_f32 v[100:101], v[100:101], v[116:117]
	v_pk_add_f32 v[108:109], v[98:99], v[110:111]
	v_pk_add_f32 v[110:111], v[96:97], v[118:119]
	v_mul_f32_e32 v96, v101, v101
	v_mul_f32_e32 v97, v103, v103
	v_mul_f32_e32 v98, v111, v111
	v_fmac_f32_e32 v96, v100, v100
	v_fmac_f32_e32 v97, v102, v102
	v_mul_f32_e32 v99, v109, v109
	v_fmac_f32_e32 v98, v110, v110
	v_add_f32_e32 v96, v96, v97
	v_add_f32_e32 v96, v98, v96
	v_fmac_f32_e32 v99, v108, v108
	v_add_f32_e32 v96, v99, v96
	v_add_f32_e32 v96, v122, v96
	ds_bpermute_b32 v97, v114, v96
	v_cvt_pk_bf16_f32 v98, v100, v101
	v_cvt_pk_bf16_f32 v99, v102, v103
	v_cvt_pk_bf16_f32 v100, v110, v111
	v_cvt_pk_bf16_f32 v101, v108, v109
	s_waitcnt lgkmcnt(0)
	v_add_f32_e32 v96, v96, v97
	ds_bpermute_b32 v97, v115, v96
	global_store_dwordx4 v[120:121], v[98:101], off offset:64
	s_waitcnt lgkmcnt(0)
	v_add_f32_e32 v96, v96, v97
	s_mov_b32 s26, 0xffff0000
	s_mov_b32 s27, 0
	v_cndmask_b32_e64 v229, v229, v96, s[26:27]
.LBB0_624:
	v_or_b32_e32 v96, 32, v136
	s_waitcnt lgkmcnt(0)
	v_ashrrev_i32_e32 v97, 31, v96
	v_lshlrev_b64 v[98:99], 12, v[96:97]
	v_lshl_add_u64 v[98:99], s[10:11], 0, v[98:99]
	v_lshl_add_u64 v[102:103], v[134:135], 1, v[98:99]
	s_nop 1
	s_waitcnt vmcnt(15)
	v_mov_b32_e32 v98, v182
	v_mov_b32_e32 v99, v183
	v_mov_b32_e32 v100, v184
	v_mov_b32_e32 v101, v185
	s_nop 0
	v_lshlrev_b32_e32 v104, 16, v98
	v_and_b32_e32 v105, 0xffff0000, v98
	v_lshlrev_b32_e32 v98, 16, v99
	v_and_b32_e32 v99, 0xffff0000, v99
	v_lshlrev_b32_e32 v106, 16, v100
	v_and_b32_e32 v107, 0xffff0000, v100
	v_lshlrev_b32_e32 v100, 16, v101
	v_and_b32_e32 v101, 0xffff0000, v101
	v_pk_add_f32 v[98:99], v[94:95], v[98:99]
	v_pk_add_f32 v[104:105], v[92:93], v[104:105]
	v_pk_add_f32 v[100:101], v[90:91], v[100:101]
	v_pk_add_f32 v[106:107], v[88:89], v[106:107]
	v_cvt_pk_bf16_f32 v88, v104, v105
	v_cvt_pk_bf16_f32 v89, v98, v99
	v_mul_f32_e32 v105, v105, v105
	v_cvt_pk_bf16_f32 v90, v106, v107
	v_cvt_pk_bf16_f32 v91, v100, v101
	s_nop 1
	s_waitcnt vmcnt(14)
	v_mov_b32_e32 v92, v186
	v_mov_b32_e32 v93, v187
	v_mov_b32_e32 v94, v188
	v_mov_b32_e32 v95, v189
	v_mul_f32_e32 v99, v99, v99
	v_mul_f32_e32 v107, v107, v107
	v_fmac_f32_e32 v105, v104, v104
	v_fmac_f32_e32 v99, v98, v98
	v_mul_f32_e32 v101, v101, v101
	v_fmac_f32_e32 v107, v106, v106
	v_add_f32_e32 v98, v105, v99
	v_fmac_f32_e32 v101, v100, v100
	v_add_f32_e32 v98, v107, v98
	v_add_f32_e32 v104, v101, v98
	global_store_dwordx4 v[102:103], v[88:91], off
	s_nop 0
	v_lshlrev_b32_e32 v98, 16, v92
	v_and_b32_e32 v99, 0xffff0000, v92
	v_lshlrev_b32_e32 v92, 16, v93
	v_and_b32_e32 v93, 0xffff0000, v93
	v_lshlrev_b32_e32 v100, 16, v94
	v_and_b32_e32 v101, 0xffff0000, v94
	v_lshlrev_b32_e32 v94, 16, v95
	v_and_b32_e32 v95, 0xffff0000, v95
	v_pk_add_f32 v[86:87], v[86:87], v[92:93]
	v_pk_add_f32 v[84:85], v[84:85], v[98:99]
	v_pk_add_f32 v[92:93], v[82:83], v[94:95]
	v_pk_add_f32 v[94:95], v[80:81], v[100:101]
	v_mul_f32_e32 v80, v85, v85
	v_mul_f32_e32 v81, v87, v87
	v_mul_f32_e32 v82, v95, v95
	v_fmac_f32_e32 v80, v84, v84
	v_fmac_f32_e32 v81, v86, v86
	v_mul_f32_e32 v83, v93, v93
	v_fmac_f32_e32 v82, v94, v94
	v_add_f32_e32 v80, v80, v81
	v_add_f32_e32 v80, v82, v80
	v_fmac_f32_e32 v83, v92, v92
	v_add_f32_e32 v80, v83, v80
	v_add_f32_e32 v80, v104, v80
	ds_bpermute_b32 v81, v114, v80
	v_cvt_pk_bf16_f32 v82, v84, v85
	v_cvt_pk_bf16_f32 v83, v86, v87
	v_cvt_pk_bf16_f32 v84, v94, v95
	v_cvt_pk_bf16_f32 v85, v92, v93
	s_waitcnt lgkmcnt(0)
	v_add_f32_e32 v80, v80, v81
	ds_bpermute_b32 v81, v115, v80
	global_store_dwordx4 v[102:103], v[82:85], off offset:64
	s_waitcnt lgkmcnt(0)
	v_add_f32_e32 v80, v80, v81
	s_mov_b32 s26, 0
	s_mov_b32 s27, 0xffff
	v_cndmask_b32_e64 v229, v229, v80, s[26:27]
; __device__ __forceinline__ u32x4 pack8(f32x4 a, f32x4 b) { u32x4 w; w.x = cvt_pk_bf16(a[0], a[1]); w.y = cvt_pk_bf16(a[2], a[3]); w.z = cvt_pk_bf16(b[0], b[1]); w.w = cvt_pk_bf16(b[2], b[3]); return w; }
;     __device__ __forceinline__ void operator()(const f32x4 (&acc)[2][2][4][2], const Unit& u, int wr, int wc, int fr, int fq) const {
;     ...
;                 const int row = row0 + ai * HALF + m * 16; const size_t off = (size_t)row * 2048 + col;
;                 float s = 0.f;
; #pragma unroll
;                 for (int bj = 0; bj < 2; ++bj) {
;                     f32x4 b0, b1;
;                     if (BASE_F32) { const float* bp = (const float*)base + off + bj * 32; b0 = *(const f32x4*)bp; b1 = *(const f32x4*)(bp + 4); }
;                     else { const u32x4 w = *(const u32x4*)((const bf16_t*)base + off + bj * 32);
;                         b0 = (f32x4){__uint_as_float(w.x << 16), __uint_as_float(w.x & 0xffff0000u), __uint_as_float(w.y << 16), __uint_as_float(w.y & 0xffff0000u)};
;                         b1 = (f32x4){__uint_as_float(w.z << 16), __uint_as_float(w.z & 0xffff0000u), __uint_as_float(w.w << 16), __uint_as_float(w.w & 0xffff0000u)}; }
;                     const f32x4 h0 = b0 + acc[ai][bj][m][0], h1 = b1 + acc[ai][bj][m][1];
;                     s += (h0[0] * h0[0] + h0[1] * h0[1]) + (h0[2] * h0[2] + h0[3] * h0[3]) + (h1[0] * h1[0] + h1[1] * h1[1]) + (h1[2] * h1[2] + h1[3] * h1[3]);
;                     *(u32x4*)(H + off + bj * 32) = pack8(h0, h1);
;                 }
;                 s += __shfl_xor(s, 16); s += __shfl_xor(s, 32);
;                 if (fq == 0) __hip_atomic_fetch_add(ss + row, s, __ATOMIC_RELAXED, __HIP_MEMORY_SCOPE_AGENT);
.LBB0_626:
	v_or_b32_e32 v80, 48, v136
	s_waitcnt lgkmcnt(0)
	v_ashrrev_i32_e32 v81, 31, v80
	v_lshlrev_b64 v[82:83], 12, v[80:81]
	v_lshl_add_u64 v[82:83], s[10:11], 0, v[82:83]
	v_lshl_add_u64 v[86:87], v[134:135], 1, v[82:83]
	s_nop 1
	s_waitcnt vmcnt(15)
	v_mov_b32_e32 v82, v190
	v_mov_b32_e32 v83, v191
	v_mov_b32_e32 v84, v192
	v_mov_b32_e32 v85, v193
	s_nop 0
	v_lshlrev_b32_e32 v88, 16, v82
	v_and_b32_e32 v89, 0xffff0000, v82
	v_lshlrev_b32_e32 v82, 16, v83
	v_and_b32_e32 v83, 0xffff0000, v83
	v_lshlrev_b32_e32 v90, 16, v84
	v_and_b32_e32 v91, 0xffff0000, v84
	v_lshlrev_b32_e32 v84, 16, v85
	v_and_b32_e32 v85, 0xffff0000, v85
	v_pk_add_f32 v[82:83], v[78:79], v[82:83]
	v_pk_add_f32 v[88:89], v[76:77], v[88:89]
	v_pk_add_f32 v[84:85], v[74:75], v[84:85]
	v_pk_add_f32 v[90:91], v[72:73], v[90:91]
	v_cvt_pk_bf16_f32 v72, v88, v89
	v_cvt_pk_bf16_f32 v73, v82, v83
	v_mul_f32_e32 v89, v89, v89
	v_cvt_pk_bf16_f32 v74, v90, v91
	v_cvt_pk_bf16_f32 v75, v84, v85
	s_nop 1
	s_waitcnt vmcnt(14)
	v_mov_b32_e32 v76, v194
	v_mov_b32_e32 v77, v195
	v_mov_b32_e32 v78, v196
	v_mov_b32_e32 v79, v197
	v_mul_f32_e32 v83, v83, v83
	v_mul_f32_e32 v91, v91, v91
	v_fmac_f32_e32 v89, v88, v88
	v_fmac_f32_e32 v83, v82, v82
	v_mul_f32_e32 v85, v85, v85
	v_fmac_f32_e32 v91, v90, v90
	v_add_f32_e32 v82, v89, v83
	v_fmac_f32_e32 v85, v84, v84
	v_add_f32_e32 v82, v91, v82
	v_add_f32_e32 v88, v85, v82
	global_store_dwordx4 v[86:87], v[72:75], off
	s_nop 0
	v_lshlrev_b32_e32 v82, 16, v76
	v_and_b32_e32 v83, 0xffff0000, v76
	v_lshlrev_b32_e32 v76, 16, v77
	v_and_b32_e32 v77, 0xffff0000, v77
	v_lshlrev_b32_e32 v84, 16, v78
	v_and_b32_e32 v85, 0xffff0000, v78
	v_lshlrev_b32_e32 v78, 16, v79
	v_and_b32_e32 v79, 0xffff0000, v79
	v_pk_add_f32 v[70:71], v[70:71], v[76:77]
	v_pk_add_f32 v[68:69], v[68:69], v[82:83]
	v_pk_add_f32 v[76:77], v[66:67], v[78:79]
	v_pk_add_f32 v[78:79], v[64:65], v[84:85]
	v_mul_f32_e32 v64, v69, v69
	v_mul_f32_e32 v65, v71, v71
	v_mul_f32_e32 v66, v79, v79
	v_fmac_f32_e32 v64, v68, v68
	v_fmac_f32_e32 v65, v70, v70
	v_mul_f32_e32 v67, v77, v77
	v_fmac_f32_e32 v66, v78, v78
	v_add_f32_e32 v64, v64, v65
	v_add_f32_e32 v64, v66, v64
	v_fmac_f32_e32 v67, v76, v76
	v_add_f32_e32 v64, v67, v64
	v_add_f32_e32 v64, v88, v64
	ds_bpermute_b32 v65, v114, v64
	v_cvt_pk_bf16_f32 v66, v68, v69
	v_cvt_pk_bf16_f32 v67, v70, v71
	v_cvt_pk_bf16_f32 v68, v78, v79
	v_cvt_pk_bf16_f32 v69, v76, v77
	s_waitcnt lgkmcnt(0)
	v_add_f32_e32 v64, v64, v65
	ds_bpermute_b32 v65, v115, v64
	global_store_dwordx4 v[86:87], v[66:69], off offset:64
	s_waitcnt lgkmcnt(0)
	v_add_f32_e32 v64, v64, v65
	s_mov_b32 s26, 0
	s_mov_b32 s27, 0xffff0000
	v_cndmask_b32_e64 v229, v229, v64, s[26:27]
	global_atomic_add_f32 v[230:231], v229, off
.LBB0_628:
	v_add_u32_e32 v64, 0x80, v136
	s_waitcnt lgkmcnt(0)
	v_ashrrev_i32_e32 v65, 31, v64
	v_lshlrev_b64 v[66:67], 12, v[64:65]
	v_lshl_add_u64 v[66:67], s[10:11], 0, v[66:67]
	v_lshl_add_u64 v[70:71], v[134:135], 1, v[66:67]
	s_nop 1
	s_waitcnt vmcnt(15)
	v_mov_b32_e32 v66, v198
	v_mov_b32_e32 v67, v199
	v_mov_b32_e32 v68, v200
	v_mov_b32_e32 v69, v201
	s_nop 0
	v_lshlrev_b32_e32 v72, 16, v66
	v_and_b32_e32 v73, 0xffff0000, v66
	v_lshlrev_b32_e32 v66, 16, v67
	v_and_b32_e32 v67, 0xffff0000, v67
	v_lshlrev_b32_e32 v74, 16, v68
	v_and_b32_e32 v75, 0xffff0000, v68
	v_lshlrev_b32_e32 v68, 16, v69
	v_and_b32_e32 v69, 0xffff0000, v69
	v_pk_add_f32 v[66:67], v[62:63], v[66:67]
	v_pk_add_f32 v[72:73], v[60:61], v[72:73]
	v_pk_add_f32 v[68:69], v[58:59], v[68:69]
	v_pk_add_f32 v[74:75], v[56:57], v[74:75]
	v_cvt_pk_bf16_f32 v56, v72, v73
	v_cvt_pk_bf16_f32 v57, v66, v67
	v_mul_f32_e32 v73, v73, v73
	v_cvt_pk_bf16_f32 v58, v74, v75
	v_cvt_pk_bf16_f32 v59, v68, v69
	s_nop 1
	s_waitcnt vmcnt(14)
	v_mov_b32_e32 v60, v212
	v_mov_b32_e32 v61, v213
	v_mov_b32_e32 v62, v214
	v_mov_b32_e32 v63, v215
	v_mul_f32_e32 v67, v67, v67
	v_mul_f32_e32 v75, v75, v75
	v_fmac_f32_e32 v73, v72, v72
	v_fmac_f32_e32 v67, v66, v66
	v_mul_f32_e32 v69, v69, v69
	v_fmac_f32_e32 v75, v74, v74
	v_add_f32_e32 v66, v73, v67
	v_fmac_f32_e32 v69, v68, v68
	v_add_f32_e32 v66, v75, v66
	v_add_f32_e32 v72, v69, v66
	global_store_dwordx4 v[70:71], v[56:59], off
	s_nop 0
	v_lshlrev_b32_e32 v66, 16, v60
	v_and_b32_e32 v67, 0xffff0000, v60
	v_lshlrev_b32_e32 v60, 16, v61
	v_and_b32_e32 v61, 0xffff0000, v61
	v_lshlrev_b32_e32 v68, 16, v62
	v_and_b32_e32 v69, 0xffff0000, v62
	v_lshlrev_b32_e32 v62, 16, v63
	v_and_b32_e32 v63, 0xffff0000, v63
	v_pk_add_f32 v[54:55], v[54:55], v[60:61]
	v_pk_add_f32 v[52:53], v[52:53], v[66:67]
	v_pk_add_f32 v[60:61], v[50:51], v[62:63]
	v_pk_add_f32 v[62:63], v[48:49], v[68:69]
	v_mul_f32_e32 v48, v53, v53
	v_mul_f32_e32 v49, v55, v55
	v_mul_f32_e32 v50, v63, v63
	v_fmac_f32_e32 v48, v52, v52
	v_fmac_f32_e32 v49, v54, v54
	v_mul_f32_e32 v51, v61, v61
	v_fmac_f32_e32 v50, v62, v62
	v_add_f32_e32 v48, v48, v49
	v_add_f32_e32 v48, v50, v48
	v_fmac_f32_e32 v51, v60, v60
	v_add_f32_e32 v48, v51, v48
	v_add_f32_e32 v48, v72, v48
	ds_bpermute_b32 v49, v114, v48
	v_cvt_pk_bf16_f32 v50, v52, v53
	v_cvt_pk_bf16_f32 v51, v54, v55
	v_cvt_pk_bf16_f32 v52, v62, v63
	v_cvt_pk_bf16_f32 v53, v60, v61
	s_waitcnt lgkmcnt(0)
	v_add_f32_e32 v48, v48, v49
	ds_bpermute_b32 v49, v115, v48
	global_store_dwordx4 v[70:71], v[50:53], off offset:64
	s_waitcnt lgkmcnt(0)
	v_add_f32_e32 v48, v48, v49
	v_mov_b32_e32 v229, v48
; __device__ __forceinline__ u32x4 pack8(f32x4 a, f32x4 b) { u32x4 w; w.x = cvt_pk_bf16(a[0], a[1]); w.y = cvt_pk_bf16(a[2], a[3]); w.z = cvt_pk_bf16(b[0], b[1]); w.w = cvt_pk_bf16(b[2], b[3]); return w; }
;     __device__ __forceinline__ void operator()(const f32x4 (&acc)[2][2][4][2], const Unit& u, int wr, int wc, int fr, int fq) const {
;     ...
;                 const int row = row0 + ai * HALF + m * 16; const size_t off = (size_t)row * 2048 + col;
;                 float s = 0.f;
; #pragma unroll
;                 for (int bj = 0; bj < 2; ++bj) {
;                     f32x4 b0, b1;
;                     if (BASE_F32) { const float* bp = (const float*)base + off + bj * 32; b0 = *(const f32x4*)bp; b1 = *(const f32x4*)(bp + 4); }
;                     else { const u32x4 w = *(const u32x4*)((const bf16_t*)base + off + bj * 32);
;                         b0 = (f32x4){__uint_as_float(w.x << 16), __uint_as_float(w.x & 0xffff0000u), __uint_as_float(w.y << 16), __uint_as_float(w.y & 0xffff0000u)};
;                         b1 = (f32x4){__uint_as_float(w.z << 16), __uint_as_float(w.z & 0xffff0000u), __uint_as_float(w.w << 16), __uint_as_float(w.w & 0xffff0000u)}; }
;                     const f32x4 h0 = b0 + acc[ai][bj][m][0], h1 = b1 + acc[ai][bj][m][1];
;                     s += (h0[0] * h0[0] + h0[1] * h0[1]) + (h0[2] * h0[2] + h0[3] * h0[3]) + (h1[0] * h1[0] + h1[1] * h1[1]) + (h1[2] * h1[2] + h1[3] * h1[3]);
;                     *(u32x4*)(H + off + bj * 32) = pack8(h0, h1);
;                 }
;                 s += __shfl_xor(s, 16); s += __shfl_xor(s, 32);
;                 if (fq == 0) __hip_atomic_fetch_add(ss + row, s, __ATOMIC_RELAXED, __HIP_MEMORY_SCOPE_AGENT);
.LBB0_630:
	v_add_u32_e32 v48, 0x90, v136
	s_waitcnt lgkmcnt(0)
	v_ashrrev_i32_e32 v49, 31, v48
	v_lshlrev_b64 v[50:51], 12, v[48:49]
	v_lshl_add_u64 v[50:51], s[10:11], 0, v[50:51]
	v_lshl_add_u64 v[54:55], v[134:135], 1, v[50:51]
	s_nop 1
	s_waitcnt vmcnt(15)
	v_mov_b32_e32 v50, v216
	v_mov_b32_e32 v51, v217
	v_mov_b32_e32 v52, v218
	v_mov_b32_e32 v53, v219
	s_nop 0
	v_lshlrev_b32_e32 v56, 16, v50
	v_and_b32_e32 v57, 0xffff0000, v50
	v_lshlrev_b32_e32 v50, 16, v51
	v_and_b32_e32 v51, 0xffff0000, v51
	v_lshlrev_b32_e32 v58, 16, v52
	v_and_b32_e32 v59, 0xffff0000, v52
	v_lshlrev_b32_e32 v52, 16, v53
	v_and_b32_e32 v53, 0xffff0000, v53
	v_pk_add_f32 v[50:51], v[46:47], v[50:51]
	v_pk_add_f32 v[56:57], v[44:45], v[56:57]
	v_pk_add_f32 v[52:53], v[42:43], v[52:53]
	v_pk_add_f32 v[58:59], v[40:41], v[58:59]
	v_cvt_pk_bf16_f32 v40, v56, v57
	v_cvt_pk_bf16_f32 v41, v50, v51
	v_mul_f32_e32 v57, v57, v57
	v_cvt_pk_bf16_f32 v42, v58, v59
	v_cvt_pk_bf16_f32 v43, v52, v53
	s_nop 1
	s_waitcnt vmcnt(14)
	v_mov_b32_e32 v44, v220
	v_mov_b32_e32 v45, v221
	v_mov_b32_e32 v46, v222
	v_mov_b32_e32 v47, v223
	v_mul_f32_e32 v51, v51, v51
	v_mul_f32_e32 v59, v59, v59
	v_fmac_f32_e32 v57, v56, v56
	v_fmac_f32_e32 v51, v50, v50
	v_mul_f32_e32 v53, v53, v53
	v_fmac_f32_e32 v59, v58, v58
	v_add_f32_e32 v50, v57, v51
	v_fmac_f32_e32 v53, v52, v52
	v_add_f32_e32 v50, v59, v50
	v_add_f32_e32 v56, v53, v50
	global_store_dwordx4 v[54:55], v[40:43], off
	s_nop 0
	v_lshlrev_b32_e32 v50, 16, v44
	v_and_b32_e32 v51, 0xffff0000, v44
	v_lshlrev_b32_e32 v44, 16, v45
	v_and_b32_e32 v45, 0xffff0000, v45
	v_lshlrev_b32_e32 v52, 16, v46
	v_and_b32_e32 v53, 0xffff0000, v46
	v_lshlrev_b32_e32 v46, 16, v47
	v_and_b32_e32 v47, 0xffff0000, v47
	v_pk_add_f32 v[38:39], v[38:39], v[44:45]
	v_pk_add_f32 v[36:37], v[36:37], v[50:51]
	v_pk_add_f32 v[44:45], v[34:35], v[46:47]
	v_pk_add_f32 v[46:47], v[32:33], v[52:53]
	v_mul_f32_e32 v32, v37, v37
	v_mul_f32_e32 v33, v39, v39
	v_mul_f32_e32 v34, v47, v47
	v_fmac_f32_e32 v32, v36, v36
	v_fmac_f32_e32 v33, v38, v38
	v_mul_f32_e32 v35, v45, v45
	v_fmac_f32_e32 v34, v46, v46
	v_add_f32_e32 v32, v32, v33
	v_add_f32_e32 v32, v34, v32
	v_fmac_f32_e32 v35, v44, v44
	v_add_f32_e32 v32, v35, v32
	v_add_f32_e32 v32, v56, v32
	ds_bpermute_b32 v33, v114, v32
	v_cvt_pk_bf16_f32 v34, v36, v37
	v_cvt_pk_bf16_f32 v35, v38, v39
	v_cvt_pk_bf16_f32 v36, v46, v47
	v_cvt_pk_bf16_f32 v37, v44, v45
	s_waitcnt lgkmcnt(0)
	v_add_f32_e32 v32, v32, v33
	ds_bpermute_b32 v33, v115, v32
	global_store_dwordx4 v[54:55], v[34:37], off offset:64
	s_waitcnt lgkmcnt(0)
	v_add_f32_e32 v32, v32, v33
	s_mov_b32 s26, 0xffff0000
	s_mov_b32 s27, 0
	v_cndmask_b32_e64 v229, v229, v32, s[26:27]
.LBB0_632:
	v_add_u32_e32 v32, 0xa0, v136
	s_waitcnt lgkmcnt(0)
	v_ashrrev_i32_e32 v33, 31, v32
	v_lshlrev_b64 v[34:35], 12, v[32:33]
	v_lshl_add_u64 v[34:35], s[10:11], 0, v[34:35]
	v_lshl_add_u64 v[38:39], v[134:135], 1, v[34:35]
	s_nop 1
	s_waitcnt vmcnt(14)
	v_mov_b32_e32 v34, v154
	v_mov_b32_e32 v35, v155
	v_mov_b32_e32 v36, v156
	v_mov_b32_e32 v37, v157
	s_nop 0
	v_lshlrev_b32_e32 v40, 16, v34
	v_and_b32_e32 v41, 0xffff0000, v34
	v_lshlrev_b32_e32 v34, 16, v35
	v_and_b32_e32 v35, 0xffff0000, v35
	v_lshlrev_b32_e32 v42, 16, v36
	v_and_b32_e32 v43, 0xffff0000, v36
	v_lshlrev_b32_e32 v36, 16, v37
	v_and_b32_e32 v37, 0xffff0000, v37
	v_pk_add_f32 v[34:35], v[30:31], v[34:35]
	v_pk_add_f32 v[40:41], v[28:29], v[40:41]
	v_pk_add_f32 v[36:37], v[26:27], v[36:37]
	v_pk_add_f32 v[42:43], v[24:25], v[42:43]
	v_cvt_pk_bf16_f32 v24, v40, v41
	v_cvt_pk_bf16_f32 v25, v34, v35
	v_mul_f32_e32 v41, v41, v41
	v_cvt_pk_bf16_f32 v26, v42, v43
	v_cvt_pk_bf16_f32 v27, v36, v37
	s_nop 1
	s_waitcnt vmcnt(13)
	v_mov_b32_e32 v28, v158
	v_mov_b32_e32 v29, v159
	v_mov_b32_e32 v30, v160
	v_mov_b32_e32 v31, v161
	v_mul_f32_e32 v35, v35, v35
	v_mul_f32_e32 v43, v43, v43
	v_fmac_f32_e32 v41, v40, v40
	v_fmac_f32_e32 v35, v34, v34
	v_mul_f32_e32 v37, v37, v37
	v_fmac_f32_e32 v43, v42, v42
	v_add_f32_e32 v34, v41, v35
	v_fmac_f32_e32 v37, v36, v36
	v_add_f32_e32 v34, v43, v34
	v_add_f32_e32 v40, v37, v34
	global_store_dwordx4 v[38:39], v[24:27], off
	s_nop 0
	v_lshlrev_b32_e32 v34, 16, v28
	v_and_b32_e32 v35, 0xffff0000, v28
	v_lshlrev_b32_e32 v28, 16, v29
	v_and_b32_e32 v29, 0xffff0000, v29
	v_lshlrev_b32_e32 v36, 16, v30
	v_and_b32_e32 v37, 0xffff0000, v30
	v_lshlrev_b32_e32 v30, 16, v31
	v_and_b32_e32 v31, 0xffff0000, v31
	v_pk_add_f32 v[22:23], v[22:23], v[28:29]
	v_pk_add_f32 v[20:21], v[20:21], v[34:35]
	v_pk_add_f32 v[28:29], v[18:19], v[30:31]
	v_pk_add_f32 v[30:31], v[16:17], v[36:37]
	v_mul_f32_e32 v16, v21, v21
	v_mul_f32_e32 v17, v23, v23
	v_mul_f32_e32 v18, v31, v31
	v_fmac_f32_e32 v16, v20, v20
	v_fmac_f32_e32 v17, v22, v22
	v_mul_f32_e32 v19, v29, v29
	v_fmac_f32_e32 v18, v30, v30
	v_add_f32_e32 v16, v16, v17
	v_add_f32_e32 v16, v18, v16
	v_fmac_f32_e32 v19, v28, v28
	v_add_f32_e32 v16, v19, v16
	v_add_f32_e32 v16, v40, v16
	ds_bpermute_b32 v17, v114, v16
	v_cvt_pk_bf16_f32 v18, v20, v21
	v_cvt_pk_bf16_f32 v19, v22, v23
	v_cvt_pk_bf16_f32 v20, v30, v31
	v_cvt_pk_bf16_f32 v21, v28, v29
	s_waitcnt lgkmcnt(0)
	v_add_f32_e32 v16, v16, v17
	ds_bpermute_b32 v17, v115, v16
	global_store_dwordx4 v[38:39], v[18:21], off offset:64
	s_waitcnt lgkmcnt(0)
	v_add_f32_e32 v16, v16, v17
	s_mov_b32 s26, 0
	s_mov_b32 s27, 0xffff
	v_cndmask_b32_e64 v229, v229, v16, s[26:27]
; #define PG8_BAR __builtin_amdgcn_s_barrier()
; template <class Epi, class Sched, bool ALIGN_EPI = false, bool SP2 = false>
; __device__ __forceinline__ void gemm_phase(PG8_LAS unsigned char* lds, const Gemm g, const Sched& S, const Epi& E) {
;     ...
;         if (!has_next) break;
; #pragma unroll
;         for (int a = 0; a < 2; ++a)
; #pragma unroll
;             for (int b = 0; b < 2; ++b)
; #pragma unroll
;                 for (int m = 0; m < 4; ++m)
; #pragma unroll
;                     for (int n = 0; n < 2; ++n) acc[a][b][m][n] = (f32x4){0.f, 0.f, 0.f, 0.f};
;         cur = nxt; cA = nA; cB = nB; st = nst; ++ui;
;         if constexpr (ALIGN_EPI) { if (wr == 1) PG8_BAR; }
;     __device__ __forceinline__ void operator()(const f32x4 (&acc)[2][2][4][2], const Unit& u, int wr, int wc, int fr, int fq) const {
;     ...
;                 const int row = row0 + ai * HALF + m * 16; const size_t off = (size_t)row * 2048 + col;
;                 float s = 0.f;
; #pragma unroll
;                 for (int bj = 0; bj < 2; ++bj) {
;                     f32x4 b0, b1;
;                     if (BASE_F32) { const float* bp = (const float*)base + off + bj * 32; b0 = *(const f32x4*)bp; b1 = *(const f32x4*)(bp + 4); }
;                     else { const u32x4 w = *(const u32x4*)((const bf16_t*)base + off + bj * 32);
;                         b0 = (f32x4){__uint_as_float(w.x << 16), __uint_as_float(w.x & 0xffff0000u), __uint_as_float(w.y << 16), __uint_as_float(w.y & 0xffff0000u)};
;                         b1 = (f32x4){__uint_as_float(w.z << 16), __uint_as_float(w.z & 0xffff0000u), __uint_as_float(w.w << 16), __uint_as_float(w.w & 0xffff0000u)}; }
;                     const f32x4 h0 = b0 + acc[ai][bj][m][0], h1 = b1 + acc[ai][bj][m][1];
;                     s += (h0[0] * h0[0] + h0[1] * h0[1]) + (h0[2] * h0[2] + h0[3] * h0[3]) + (h1[0] * h1[0] + h1[1] * h1[1]) + (h1[2] * h1[2] + h1[3] * h1[3]);
;                     *(u32x4*)(H + off + bj * 32) = pack8(h0, h1);
;                 }
;                 s += __shfl_xor(s, 16); s += __shfl_xor(s, 32);
;                 if (fq == 0) __hip_atomic_fetch_add(ss + row, s, __ATOMIC_RELAXED, __HIP_MEMORY_SCOPE_AGENT);
;                 if (m & 1) asm volatile("" ::: "memory");
;             }
.LBB0_634:
	v_add_u32_e32 v16, 0xb0, v136
	s_waitcnt lgkmcnt(0)
	v_ashrrev_i32_e32 v17, 31, v16
	v_lshlrev_b64 v[18:19], 12, v[16:17]
	v_lshl_add_u64 v[18:19], s[10:11], 0, v[18:19]
	v_lshl_add_u64 v[22:23], v[134:135], 1, v[18:19]
	s_nop 1
	s_waitcnt vmcnt(13)
	v_mov_b32_e32 v18, v162
	v_mov_b32_e32 v19, v163
	v_mov_b32_e32 v20, v164
	v_mov_b32_e32 v21, v165
	s_nop 0
	v_lshlrev_b32_e32 v24, 16, v18
	v_and_b32_e32 v25, 0xffff0000, v18
	v_lshlrev_b32_e32 v18, 16, v19
	v_and_b32_e32 v19, 0xffff0000, v19
	v_lshlrev_b32_e32 v26, 16, v20
	v_and_b32_e32 v27, 0xffff0000, v20
	v_lshlrev_b32_e32 v20, 16, v21
	v_and_b32_e32 v21, 0xffff0000, v21
	v_pk_add_f32 v[18:19], v[14:15], v[18:19]
	v_pk_add_f32 v[24:25], v[12:13], v[24:25]
	v_pk_add_f32 v[20:21], v[10:11], v[20:21]
	v_pk_add_f32 v[26:27], v[8:9], v[26:27]
	v_cvt_pk_bf16_f32 v8, v24, v25
	v_cvt_pk_bf16_f32 v9, v18, v19
	v_mul_f32_e32 v25, v25, v25
	v_cvt_pk_bf16_f32 v10, v26, v27
	v_cvt_pk_bf16_f32 v11, v20, v21
	s_nop 1
	s_waitcnt vmcnt(12)
	v_mov_b32_e32 v12, v166
	v_mov_b32_e32 v13, v167
	v_mov_b32_e32 v14, v168
	v_mov_b32_e32 v15, v169
	v_mul_f32_e32 v19, v19, v19
	v_mul_f32_e32 v27, v27, v27
	v_fmac_f32_e32 v25, v24, v24
	v_fmac_f32_e32 v19, v18, v18
	v_mul_f32_e32 v21, v21, v21
	v_fmac_f32_e32 v27, v26, v26
	v_add_f32_e32 v18, v25, v19
	v_fmac_f32_e32 v21, v20, v20
	v_add_f32_e32 v18, v27, v18
	v_add_f32_e32 v24, v21, v18
	global_store_dwordx4 v[22:23], v[8:11], off
	s_nop 0
	v_lshlrev_b32_e32 v18, 16, v12
	v_and_b32_e32 v19, 0xffff0000, v12
	v_lshlrev_b32_e32 v12, 16, v13
	v_and_b32_e32 v13, 0xffff0000, v13
	v_lshlrev_b32_e32 v20, 16, v14
	v_and_b32_e32 v21, 0xffff0000, v14
	v_lshlrev_b32_e32 v14, 16, v15
	v_and_b32_e32 v15, 0xffff0000, v15
	v_pk_add_f32 v[6:7], v[6:7], v[12:13]
	v_pk_add_f32 v[4:5], v[4:5], v[18:19]
	v_pk_add_f32 v[12:13], v[2:3], v[14:15]
	v_pk_add_f32 v[14:15], v[0:1], v[20:21]
	v_mul_f32_e32 v0, v5, v5
	v_mul_f32_e32 v1, v7, v7
	v_mul_f32_e32 v2, v15, v15
	v_fmac_f32_e32 v0, v4, v4
	v_fmac_f32_e32 v1, v6, v6
	v_mul_f32_e32 v3, v13, v13
	v_fmac_f32_e32 v2, v14, v14
	v_add_f32_e32 v0, v0, v1
	v_add_f32_e32 v0, v2, v0
	v_fmac_f32_e32 v3, v12, v12
	v_add_f32_e32 v0, v3, v0
	v_add_f32_e32 v0, v24, v0
	ds_bpermute_b32 v1, v114, v0
	v_cvt_pk_bf16_f32 v2, v4, v5
	v_cvt_pk_bf16_f32 v3, v6, v7
	v_cvt_pk_bf16_f32 v4, v14, v15
	v_cvt_pk_bf16_f32 v5, v12, v13
	s_waitcnt lgkmcnt(0)
	v_add_f32_e32 v0, v0, v1
	ds_bpermute_b32 v1, v115, v0
	global_store_dwordx4 v[22:23], v[2:5], off offset:64
	s_waitcnt lgkmcnt(0)
	v_add_f32_e32 v0, v0, v1
	s_mov_b32 s26, 0
	s_mov_b32 s27, 0xffff0000
	v_cndmask_b32_e64 v229, v229, v0, s[26:27]
	global_atomic_add_f32 v[230:231], v229, off offset:512
.LBB0_636:
	s_andn2_b64 vcc, exec, s[4:5]
	s_mov_b64 s[4:5], -1
	s_cbranch_vccnz .LBB0_605
	s_andn2_b64 vcc, exec, s[8:9]
	s_cbranch_vccnz .LBB0_604
	s_barrier
	s_branch .LBB0_604

; __device__ __forceinline__ u32x4 pack8(f32x4 a, f32x4 b) { u32x4 w; w.x = cvt_pk_bf16(a[0], a[1]); w.y = cvt_pk_bf16(a[2], a[3]); w.z = cvt_pk_bf16(b[0], b[1]); w.w = cvt_pk_bf16(b[2], b[3]); return w; }
;     __device__ __forceinline__ void operator()(const f32x4 (&acc)[2][2][4][2], const Unit& u, int wr, int wc, int fr, int fq) const {
;         const int row0 = u.pm * BM + wr * 64 + fr, col = u.pn * BM + wc * 64 + 8 * fq;
; #pragma unroll
;         for (int ai = 0; ai < 2; ++ai)
; #pragma unroll
;             for (int m = 0; m < 4; ++m) {
;                 const int row = row0 + ai * HALF + m * 16; const size_t off = (size_t)row * 2048 + col;
;                 float s = 0.f;
; #pragma unroll
;                 for (int bj = 0; bj < 2; ++bj) {
;                     f32x4 b0, b1;
;                     if (BASE_F32) { const float* bp = (const float*)base + off + bj * 32; b0 = *(const f32x4*)bp; b1 = *(const f32x4*)(bp + 4); }
;                     else { const u32x4 w = *(const u32x4*)((const bf16_t*)base + off + bj * 32);
;                         b0 = (f32x4){__uint_as_float(w.x << 16), __uint_as_float(w.x & 0xffff0000u), __uint_as_float(w.y << 16), __uint_as_float(w.y & 0xffff0000u)};
;                         b1 = (f32x4){__uint_as_float(w.z << 16), __uint_as_float(w.z & 0xffff0000u), __uint_as_float(w.w << 16), __uint_as_float(w.w & 0xffff0000u)}; }
;                     const f32x4 h0 = b0 + acc[ai][bj][m][0], h1 = b1 + acc[ai][bj][m][1];
;                     s += (h0[0] * h0[0] + h0[1] * h0[1]) + (h0[2] * h0[2] + h0[3] * h0[3]) + (h1[0] * h1[0] + h1[1] * h1[1]) + (h1[2] * h1[2] + h1[3] * h1[3]);
;                     *(u32x4*)(H + off + bj * 32) = pack8(h0, h1);
;                 }
;                 s += __shfl_xor(s, 16); s += __shfl_xor(s, 32);
.LBB0_798:
	v_lshl_add_u32 v138, s24, 8, v141
	v_ashrrev_i32_e32 v139, 31, v138
	v_lshl_or_b32 v136, s26, 8, v143
	v_lshlrev_b64 v[134:135], 12, v[138:139]
	v_ashrrev_i32_e32 v137, 31, v136
	v_lshl_add_u64 v[134:135], s[8:9], 0, v[134:135]
	v_lshl_add_u64 v[134:135], v[136:137], 1, v[134:135]
	v_mov_b32_e32 v220, v138
	v_ashrrev_i32_e32 v221, 31, v220
	v_lshlrev_b64 v[220:221], 12, v[220:221]
	v_lshl_add_u64 v[220:221], s[8:9], 0, v[220:221]
	v_lshl_add_u64 v[220:221], v[136:137], 1, v[220:221]
	global_load_dwordx4 v[154:157], v[220:221], off
	global_load_dwordx4 v[158:161], v[220:221], off offset:64
	v_add_u32_e32 v220, 0x10, v138
	v_ashrrev_i32_e32 v221, 31, v220
	v_lshlrev_b64 v[220:221], 12, v[220:221]
	v_lshl_add_u64 v[220:221], s[8:9], 0, v[220:221]
	v_lshl_add_u64 v[220:221], v[136:137], 1, v[220:221]
	global_load_dwordx4 v[162:165], v[220:221], off
	global_load_dwordx4 v[166:169], v[220:221], off offset:64
	v_add_u32_e32 v220, 0x20, v138
	v_ashrrev_i32_e32 v221, 31, v220
	v_lshlrev_b64 v[220:221], 12, v[220:221]
	v_lshl_add_u64 v[220:221], s[8:9], 0, v[220:221]
	v_lshl_add_u64 v[220:221], v[136:137], 1, v[220:221]
	global_load_dwordx4 v[178:181], v[220:221], off
	global_load_dwordx4 v[182:185], v[220:221], off offset:64
	v_add_u32_e32 v220, 0x30, v138
	v_ashrrev_i32_e32 v221, 31, v220
	v_lshlrev_b64 v[220:221], 12, v[220:221]
	v_lshl_add_u64 v[220:221], s[8:9], 0, v[220:221]
	v_lshl_add_u64 v[220:221], v[136:137], 1, v[220:221]
	global_load_dwordx4 v[186:189], v[220:221], off
	global_load_dwordx4 v[190:193], v[220:221], off offset:64
	v_add_u32_e32 v220, 0x80, v138
	v_ashrrev_i32_e32 v221, 31, v220
	v_lshlrev_b64 v[220:221], 12, v[220:221]
	v_lshl_add_u64 v[220:221], s[8:9], 0, v[220:221]
	v_lshl_add_u64 v[220:221], v[136:137], 1, v[220:221]
	global_load_dwordx4 v[194:197], v[220:221], off
	global_load_dwordx4 v[198:201], v[220:221], off offset:64
	v_add_u32_e32 v220, 0x90, v138
	v_ashrrev_i32_e32 v221, 31, v220
	v_lshlrev_b64 v[220:221], 12, v[220:221]
	v_lshl_add_u64 v[220:221], s[8:9], 0, v[220:221]
	v_lshl_add_u64 v[220:221], v[136:137], 1, v[220:221]
	global_load_dwordx4 v[212:215], v[220:221], off
	global_load_dwordx4 v[216:219], v[220:221], off offset:64
	v_and_b32_e32 v230, 48, v209
	v_add_u32_e32 v230, v230, v138
	v_mov_b32_e32 v231, 0
	v_lshl_add_u64 v[230:231], v[230:231], 2, s[10:11]
	s_nop 1
	s_waitcnt vmcnt(11)
	v_mov_b32_e32 v146, v154
	v_mov_b32_e32 v147, v155
	v_mov_b32_e32 v148, v156
	v_mov_b32_e32 v149, v157
	s_nop 0
	v_lshlrev_b32_e32 v150, 16, v146
	v_and_b32_e32 v151, 0xffff0000, v146
	v_lshlrev_b32_e32 v146, 16, v147
	v_and_b32_e32 v147, 0xffff0000, v147
	v_lshlrev_b32_e32 v152, 16, v148
	v_and_b32_e32 v153, 0xffff0000, v148
	v_lshlrev_b32_e32 v148, 16, v149
	v_and_b32_e32 v149, 0xffff0000, v149
	v_pk_add_f32 v[126:127], v[126:127], v[146:147]
	v_pk_add_f32 v[124:125], v[124:125], v[150:151]
	v_pk_add_f32 v[146:147], v[122:123], v[148:149]
	v_pk_add_f32 v[122:123], v[120:121], v[152:153]
	v_mul_f32_e32 v120, v125, v125
	v_mul_f32_e32 v121, v127, v127
	v_fmac_f32_e32 v120, v124, v124
	v_fmac_f32_e32 v121, v126, v126
	v_add_f32_e32 v120, v120, v121
	v_mul_f32_e32 v121, v123, v123
	v_fmac_f32_e32 v121, v122, v122
	v_add_f32_e32 v120, v121, v120
	v_mul_f32_e32 v121, v147, v147
	v_fmac_f32_e32 v121, v146, v146
	v_add_f32_e32 v145, v121, v120
	v_cvt_pk_bf16_f32 v120, v124, v125
	v_cvt_pk_bf16_f32 v121, v126, v127
	v_cvt_pk_bf16_f32 v122, v122, v123
	v_cvt_pk_bf16_f32 v123, v146, v147
	global_store_dwordx4 v[134:135], v[120:123], off
	s_nop 1
	s_waitcnt vmcnt(11)
	v_mov_b32_e32 v120, v158
	v_mov_b32_e32 v121, v159
	v_mov_b32_e32 v122, v160
	v_mov_b32_e32 v123, v161
	v_add_u32_e32 v220, 0xa0, v138
	v_ashrrev_i32_e32 v221, 31, v220
	v_lshlrev_b64 v[220:221], 12, v[220:221]
	v_lshl_add_u64 v[220:221], s[8:9], 0, v[220:221]
	v_lshl_add_u64 v[220:221], v[136:137], 1, v[220:221]
	global_load_dwordx4 v[154:157], v[220:221], off
	global_load_dwordx4 v[158:161], v[220:221], off offset:64
	s_nop 0
	v_lshlrev_b32_e32 v124, 16, v120
	v_and_b32_e32 v125, 0xffff0000, v120
	v_lshlrev_b32_e32 v120, 16, v121
	v_and_b32_e32 v121, 0xffff0000, v121
	v_lshlrev_b32_e32 v126, 16, v122
	v_and_b32_e32 v127, 0xffff0000, v122
	v_lshlrev_b32_e32 v122, 16, v123
	v_and_b32_e32 v123, 0xffff0000, v123
	v_pk_add_f32 v[118:119], v[118:119], v[120:121]
	v_pk_add_f32 v[116:117], v[116:117], v[124:125]
	v_pk_add_f32 v[120:121], v[114:115], v[122:123]
	v_pk_add_f32 v[114:115], v[112:113], v[126:127]
	v_mul_f32_e32 v112, v117, v117
	v_mul_f32_e32 v113, v119, v119
	v_fmac_f32_e32 v112, v116, v116
	v_fmac_f32_e32 v113, v118, v118
	v_add_f32_e32 v112, v112, v113
	v_mul_f32_e32 v113, v115, v115
	v_fmac_f32_e32 v113, v114, v114
	v_add_f32_e32 v112, v113, v112
	v_mul_f32_e32 v113, v121, v121
	v_fmac_f32_e32 v113, v120, v120
	v_add_f32_e32 v112, v113, v112
	v_add_f32_e32 v122, v145, v112
	v_cvt_pk_bf16_f32 v112, v116, v117
	v_cvt_pk_bf16_f32 v113, v118, v119
	v_cvt_pk_bf16_f32 v114, v114, v115
	v_cvt_pk_bf16_f32 v115, v120, v121
	global_store_dwordx4 v[134:135], v[112:115], off offset:64
	s_nop 1
	v_and_b32_e32 v113, 64, v209
	v_xor_b32_e32 v112, 16, v209
	v_add_u32_e32 v113, 64, v113
	v_cmp_lt_i32_e32 vcc, v112, v113
	s_nop 1
	v_cndmask_b32_e32 v112, v209, v112, vcc
	v_lshlrev_b32_e32 v114, 2, v112
	ds_bpermute_b32 v112, v114, v122
	s_waitcnt lgkmcnt(0)
	v_add_f32_e32 v116, v122, v112
	v_xor_b32_e32 v112, 32, v209
	v_cmp_lt_i32_e32 vcc, v112, v113
	s_nop 1
	v_cndmask_b32_e32 v112, v209, v112, vcc
	v_lshlrev_b32_e32 v115, 2, v112
	ds_bpermute_b32 v117, v115, v116
	v_lshl_add_u64 v[112:113], v[138:139], 2, s[10:11]
	s_waitcnt lgkmcnt(0)
	v_add_f32_e32 v116, v116, v117
	v_mov_b32_e32 v229, v116
; __device__ __forceinline__ u32x4 pack8(f32x4 a, f32x4 b) { u32x4 w; w.x = cvt_pk_bf16(a[0], a[1]); w.y = cvt_pk_bf16(a[2], a[3]); w.z = cvt_pk_bf16(b[0], b[1]); w.w = cvt_pk_bf16(b[2], b[3]); return w; }
;     __device__ __forceinline__ void operator()(const f32x4 (&acc)[2][2][4][2], const Unit& u, int wr, int wc, int fr, int fq) const {
;     ...
;                 const int row = row0 + ai * HALF + m * 16; const size_t off = (size_t)row * 2048 + col;
;                 float s = 0.f;
; #pragma unroll
;                 for (int bj = 0; bj < 2; ++bj) {
;                     f32x4 b0, b1;
;                     if (BASE_F32) { const float* bp = (const float*)base + off + bj * 32; b0 = *(const f32x4*)bp; b1 = *(const f32x4*)(bp + 4); }
;                     else { const u32x4 w = *(const u32x4*)((const bf16_t*)base + off + bj * 32);
;                         b0 = (f32x4){__uint_as_float(w.x << 16), __uint_as_float(w.x & 0xffff0000u), __uint_as_float(w.y << 16), __uint_as_float(w.y & 0xffff0000u)};
;                         b1 = (f32x4){__uint_as_float(w.z << 16), __uint_as_float(w.z & 0xffff0000u), __uint_as_float(w.w << 16), __uint_as_float(w.w & 0xffff0000u)}; }
;                     const f32x4 h0 = b0 + acc[ai][bj][m][0], h1 = b1 + acc[ai][bj][m][1];
;                     s += (h0[0] * h0[0] + h0[1] * h0[1]) + (h0[2] * h0[2] + h0[3] * h0[3]) + (h1[0] * h1[0] + h1[1] * h1[1]) + (h1[2] * h1[2] + h1[3] * h1[3]);
;                     *(u32x4*)(H + off + bj * 32) = pack8(h0, h1);
;                 }
;                 s += __shfl_xor(s, 16); s += __shfl_xor(s, 32);
;                 if (fq == 0) __hip_atomic_fetch_add(ss + row, s, __ATOMIC_RELAXED, __HIP_MEMORY_SCOPE_AGENT);
.LBB0_800:
	v_or_b32_e32 v116, 16, v138
	s_waitcnt lgkmcnt(0)
	v_ashrrev_i32_e32 v117, 31, v116
	v_lshlrev_b64 v[116:117], 12, v[116:117]
	v_lshl_add_u64 v[116:117], s[8:9], 0, v[116:117]
	v_lshl_add_u64 v[120:121], v[136:137], 1, v[116:117]
	s_nop 1
	s_waitcnt vmcnt(13)
	v_mov_b32_e32 v116, v162
	v_mov_b32_e32 v117, v163
	v_mov_b32_e32 v118, v164
	v_mov_b32_e32 v119, v165
	s_nop 0
	v_lshlrev_b32_e32 v122, 16, v116
	v_and_b32_e32 v123, 0xffff0000, v116
	v_lshlrev_b32_e32 v116, 16, v117
	v_and_b32_e32 v117, 0xffff0000, v117
	v_lshlrev_b32_e32 v124, 16, v118
	v_and_b32_e32 v125, 0xffff0000, v118
	v_lshlrev_b32_e32 v118, 16, v119
	v_and_b32_e32 v119, 0xffff0000, v119
	v_pk_add_f32 v[116:117], v[110:111], v[116:117]
	v_pk_add_f32 v[122:123], v[108:109], v[122:123]
	v_pk_add_f32 v[118:119], v[106:107], v[118:119]
	v_pk_add_f32 v[124:125], v[104:105], v[124:125]
	v_cvt_pk_bf16_f32 v104, v122, v123
	v_cvt_pk_bf16_f32 v105, v116, v117
	v_mul_f32_e32 v123, v123, v123
	v_cvt_pk_bf16_f32 v106, v124, v125
	v_cvt_pk_bf16_f32 v107, v118, v119
	s_nop 1
	s_waitcnt vmcnt(12)
	v_mov_b32_e32 v108, v166
	v_mov_b32_e32 v109, v167
	v_mov_b32_e32 v110, v168
	v_mov_b32_e32 v111, v169
	v_add_u32_e32 v220, 0xb0, v138
	v_ashrrev_i32_e32 v221, 31, v220
	v_lshlrev_b64 v[220:221], 12, v[220:221]
	v_lshl_add_u64 v[220:221], s[8:9], 0, v[220:221]
	v_lshl_add_u64 v[220:221], v[136:137], 1, v[220:221]
	global_load_dwordx4 v[162:165], v[220:221], off
	global_load_dwordx4 v[166:169], v[220:221], off offset:64
	v_mul_f32_e32 v117, v117, v117
	v_mul_f32_e32 v125, v125, v125
	v_fmac_f32_e32 v123, v122, v122
	v_fmac_f32_e32 v117, v116, v116
	v_mul_f32_e32 v119, v119, v119
	v_fmac_f32_e32 v125, v124, v124
	v_add_f32_e32 v116, v123, v117
	v_fmac_f32_e32 v119, v118, v118
	v_add_f32_e32 v116, v125, v116
	v_add_f32_e32 v122, v119, v116
	global_store_dwordx4 v[120:121], v[104:107], off
	s_nop 0
	v_lshlrev_b32_e32 v116, 16, v108
	v_and_b32_e32 v117, 0xffff0000, v108
	v_lshlrev_b32_e32 v108, 16, v109
	v_and_b32_e32 v109, 0xffff0000, v109
	v_lshlrev_b32_e32 v118, 16, v110
	v_and_b32_e32 v119, 0xffff0000, v110
	v_lshlrev_b32_e32 v110, 16, v111
	v_and_b32_e32 v111, 0xffff0000, v111
	v_pk_add_f32 v[102:103], v[102:103], v[108:109]
	v_pk_add_f32 v[100:101], v[100:101], v[116:117]
	v_pk_add_f32 v[108:109], v[98:99], v[110:111]
	v_pk_add_f32 v[110:111], v[96:97], v[118:119]
	v_mul_f32_e32 v96, v101, v101
	v_mul_f32_e32 v97, v103, v103
	v_mul_f32_e32 v98, v111, v111
	v_fmac_f32_e32 v96, v100, v100
	v_fmac_f32_e32 v97, v102, v102
	v_mul_f32_e32 v99, v109, v109
	v_fmac_f32_e32 v98, v110, v110
	v_add_f32_e32 v96, v96, v97
	v_add_f32_e32 v96, v98, v96
	v_fmac_f32_e32 v99, v108, v108
	v_add_f32_e32 v96, v99, v96
	v_add_f32_e32 v96, v122, v96
	ds_bpermute_b32 v97, v114, v96
	v_cvt_pk_bf16_f32 v98, v100, v101
	v_cvt_pk_bf16_f32 v99, v102, v103
	v_cvt_pk_bf16_f32 v100, v110, v111
	v_cvt_pk_bf16_f32 v101, v108, v109
	s_waitcnt lgkmcnt(0)
	v_add_f32_e32 v96, v96, v97
	ds_bpermute_b32 v97, v115, v96
	global_store_dwordx4 v[120:121], v[98:101], off offset:64
	s_waitcnt lgkmcnt(0)
	v_add_f32_e32 v96, v96, v97
	s_mov_b32 s24, 0xffff0000
	s_mov_b32 s25, 0
	v_cndmask_b32_e64 v229, v229, v96, s[24:25]
.LBB0_802:
	v_or_b32_e32 v96, 32, v138
	s_waitcnt lgkmcnt(0)
	v_ashrrev_i32_e32 v97, 31, v96
	v_lshlrev_b64 v[96:97], 12, v[96:97]
	v_lshl_add_u64 v[96:97], s[8:9], 0, v[96:97]
	v_lshl_add_u64 v[100:101], v[136:137], 1, v[96:97]
	s_nop 1
	s_waitcnt vmcnt(15)
	v_mov_b32_e32 v96, v178
	v_mov_b32_e32 v97, v179
	v_mov_b32_e32 v98, v180
	v_mov_b32_e32 v99, v181
	s_nop 0
	v_lshlrev_b32_e32 v102, 16, v96
	v_and_b32_e32 v103, 0xffff0000, v96
	v_lshlrev_b32_e32 v96, 16, v97
	v_and_b32_e32 v97, 0xffff0000, v97
	v_lshlrev_b32_e32 v104, 16, v98
	v_and_b32_e32 v105, 0xffff0000, v98
	v_lshlrev_b32_e32 v98, 16, v99
	v_and_b32_e32 v99, 0xffff0000, v99
	v_pk_add_f32 v[96:97], v[94:95], v[96:97]
	v_pk_add_f32 v[102:103], v[92:93], v[102:103]
	v_pk_add_f32 v[98:99], v[90:91], v[98:99]
	v_pk_add_f32 v[104:105], v[88:89], v[104:105]
	v_cvt_pk_bf16_f32 v88, v102, v103
	v_cvt_pk_bf16_f32 v89, v96, v97
	v_mul_f32_e32 v103, v103, v103
	v_cvt_pk_bf16_f32 v90, v104, v105
	v_cvt_pk_bf16_f32 v91, v98, v99
	s_nop 1
	s_waitcnt vmcnt(14)
	v_mov_b32_e32 v92, v182
	v_mov_b32_e32 v93, v183
	v_mov_b32_e32 v94, v184
	v_mov_b32_e32 v95, v185
	v_mul_f32_e32 v97, v97, v97
	v_mul_f32_e32 v105, v105, v105
	v_fmac_f32_e32 v103, v102, v102
	v_fmac_f32_e32 v97, v96, v96
	v_mul_f32_e32 v99, v99, v99
	v_fmac_f32_e32 v105, v104, v104
	v_add_f32_e32 v96, v103, v97
	v_fmac_f32_e32 v99, v98, v98
	v_add_f32_e32 v96, v105, v96
	v_add_f32_e32 v102, v99, v96
	global_store_dwordx4 v[100:101], v[88:91], off
	s_nop 0
	v_lshlrev_b32_e32 v96, 16, v92
	v_and_b32_e32 v97, 0xffff0000, v92
	v_lshlrev_b32_e32 v92, 16, v93
	v_and_b32_e32 v93, 0xffff0000, v93
	v_lshlrev_b32_e32 v98, 16, v94
	v_and_b32_e32 v99, 0xffff0000, v94
	v_lshlrev_b32_e32 v94, 16, v95
	v_and_b32_e32 v95, 0xffff0000, v95
	v_pk_add_f32 v[86:87], v[86:87], v[92:93]
	v_pk_add_f32 v[84:85], v[84:85], v[96:97]
	v_pk_add_f32 v[92:93], v[82:83], v[94:95]
	v_pk_add_f32 v[94:95], v[80:81], v[98:99]
	v_mul_f32_e32 v80, v85, v85
	v_mul_f32_e32 v81, v87, v87
	v_mul_f32_e32 v82, v95, v95
	v_fmac_f32_e32 v80, v84, v84
	v_fmac_f32_e32 v81, v86, v86
	v_mul_f32_e32 v83, v93, v93
	v_fmac_f32_e32 v82, v94, v94
	v_add_f32_e32 v80, v80, v81
	v_add_f32_e32 v80, v82, v80
	v_fmac_f32_e32 v83, v92, v92
	v_add_f32_e32 v80, v83, v80
	v_add_f32_e32 v80, v102, v80
	ds_bpermute_b32 v81, v114, v80
	v_cvt_pk_bf16_f32 v82, v84, v85
	v_cvt_pk_bf16_f32 v83, v86, v87
	v_cvt_pk_bf16_f32 v84, v94, v95
	v_cvt_pk_bf16_f32 v85, v92, v93
	s_waitcnt lgkmcnt(0)
	v_add_f32_e32 v80, v80, v81
	ds_bpermute_b32 v81, v115, v80
	global_store_dwordx4 v[100:101], v[82:85], off offset:64
	s_waitcnt lgkmcnt(0)
	v_add_f32_e32 v80, v80, v81
	s_mov_b32 s24, 0
	s_mov_b32 s25, 0xffff
	v_cndmask_b32_e64 v229, v229, v80, s[24:25]
; __device__ __forceinline__ u32x4 pack8(f32x4 a, f32x4 b) { u32x4 w; w.x = cvt_pk_bf16(a[0], a[1]); w.y = cvt_pk_bf16(a[2], a[3]); w.z = cvt_pk_bf16(b[0], b[1]); w.w = cvt_pk_bf16(b[2], b[3]); return w; }
;     __device__ __forceinline__ void operator()(const f32x4 (&acc)[2][2][4][2], const Unit& u, int wr, int wc, int fr, int fq) const {
;     ...
;                 const int row = row0 + ai * HALF + m * 16; const size_t off = (size_t)row * 2048 + col;
;                 float s = 0.f;
; #pragma unroll
;                 for (int bj = 0; bj < 2; ++bj) {
;                     f32x4 b0, b1;
;                     if (BASE_F32) { const float* bp = (const float*)base + off + bj * 32; b0 = *(const f32x4*)bp; b1 = *(const f32x4*)(bp + 4); }
;                     else { const u32x4 w = *(const u32x4*)((const bf16_t*)base + off + bj * 32);
;                         b0 = (f32x4){__uint_as_float(w.x << 16), __uint_as_float(w.x & 0xffff0000u), __uint_as_float(w.y << 16), __uint_as_float(w.y & 0xffff0000u)};
;                         b1 = (f32x4){__uint_as_float(w.z << 16), __uint_as_float(w.z & 0xffff0000u), __uint_as_float(w.w << 16), __uint_as_float(w.w & 0xffff0000u)}; }
;                     const f32x4 h0 = b0 + acc[ai][bj][m][0], h1 = b1 + acc[ai][bj][m][1];
;                     s += (h0[0] * h0[0] + h0[1] * h0[1]) + (h0[2] * h0[2] + h0[3] * h0[3]) + (h1[0] * h1[0] + h1[1] * h1[1]) + (h1[2] * h1[2] + h1[3] * h1[3]);
;                     *(u32x4*)(H + off + bj * 32) = pack8(h0, h1);
;                 }
;                 s += __shfl_xor(s, 16); s += __shfl_xor(s, 32);
;                 if (fq == 0) __hip_atomic_fetch_add(ss + row, s, __ATOMIC_RELAXED, __HIP_MEMORY_SCOPE_AGENT);
.LBB0_804:
	v_or_b32_e32 v80, 48, v138
	s_waitcnt lgkmcnt(0)
	v_ashrrev_i32_e32 v81, 31, v80
	v_lshlrev_b64 v[80:81], 12, v[80:81]
	v_lshl_add_u64 v[80:81], s[8:9], 0, v[80:81]
	v_lshl_add_u64 v[84:85], v[136:137], 1, v[80:81]
	s_nop 1
	s_waitcnt vmcnt(15)
	v_mov_b32_e32 v80, v186
	v_mov_b32_e32 v81, v187
	v_mov_b32_e32 v82, v188
	v_mov_b32_e32 v83, v189
	s_nop 0
	v_lshlrev_b32_e32 v86, 16, v80
	v_and_b32_e32 v87, 0xffff0000, v80
	v_lshlrev_b32_e32 v80, 16, v81
	v_and_b32_e32 v81, 0xffff0000, v81
	v_lshlrev_b32_e32 v88, 16, v82
	v_and_b32_e32 v89, 0xffff0000, v82
	v_lshlrev_b32_e32 v82, 16, v83
	v_and_b32_e32 v83, 0xffff0000, v83
	v_pk_add_f32 v[80:81], v[78:79], v[80:81]
	v_pk_add_f32 v[86:87], v[76:77], v[86:87]
	v_pk_add_f32 v[82:83], v[74:75], v[82:83]
	v_pk_add_f32 v[88:89], v[72:73], v[88:89]
	v_cvt_pk_bf16_f32 v72, v86, v87
	v_cvt_pk_bf16_f32 v73, v80, v81
	v_mul_f32_e32 v87, v87, v87
	v_cvt_pk_bf16_f32 v74, v88, v89
	v_cvt_pk_bf16_f32 v75, v82, v83
	s_nop 1
	s_waitcnt vmcnt(14)
	v_mov_b32_e32 v76, v190
	v_mov_b32_e32 v77, v191
	v_mov_b32_e32 v78, v192
	v_mov_b32_e32 v79, v193
	v_mul_f32_e32 v81, v81, v81
	v_mul_f32_e32 v89, v89, v89
	v_fmac_f32_e32 v87, v86, v86
	v_fmac_f32_e32 v81, v80, v80
	v_mul_f32_e32 v83, v83, v83
	v_fmac_f32_e32 v89, v88, v88
	v_add_f32_e32 v80, v87, v81
	v_fmac_f32_e32 v83, v82, v82
	v_add_f32_e32 v80, v89, v80
	v_add_f32_e32 v86, v83, v80
	global_store_dwordx4 v[84:85], v[72:75], off
	s_nop 0
	v_lshlrev_b32_e32 v80, 16, v76
	v_and_b32_e32 v81, 0xffff0000, v76
	v_lshlrev_b32_e32 v76, 16, v77
	v_and_b32_e32 v77, 0xffff0000, v77
	v_lshlrev_b32_e32 v82, 16, v78
	v_and_b32_e32 v83, 0xffff0000, v78
	v_lshlrev_b32_e32 v78, 16, v79
	v_and_b32_e32 v79, 0xffff0000, v79
	v_pk_add_f32 v[70:71], v[70:71], v[76:77]
	v_pk_add_f32 v[68:69], v[68:69], v[80:81]
	v_pk_add_f32 v[76:77], v[66:67], v[78:79]
	v_pk_add_f32 v[78:79], v[64:65], v[82:83]
	v_mul_f32_e32 v64, v69, v69
	v_mul_f32_e32 v65, v71, v71
	v_mul_f32_e32 v66, v79, v79
	v_fmac_f32_e32 v64, v68, v68
	v_fmac_f32_e32 v65, v70, v70
	v_mul_f32_e32 v67, v77, v77
	v_fmac_f32_e32 v66, v78, v78
	v_add_f32_e32 v64, v64, v65
	v_add_f32_e32 v64, v66, v64
	v_fmac_f32_e32 v67, v76, v76
	v_add_f32_e32 v64, v67, v64
	v_add_f32_e32 v64, v86, v64
	ds_bpermute_b32 v65, v114, v64
	v_cvt_pk_bf16_f32 v66, v68, v69
	v_cvt_pk_bf16_f32 v67, v70, v71
	v_cvt_pk_bf16_f32 v68, v78, v79
	v_cvt_pk_bf16_f32 v69, v76, v77
	s_waitcnt lgkmcnt(0)
	v_add_f32_e32 v64, v64, v65
	ds_bpermute_b32 v65, v115, v64
	global_store_dwordx4 v[84:85], v[66:69], off offset:64
	s_waitcnt lgkmcnt(0)
	v_add_f32_e32 v64, v64, v65
	s_mov_b32 s24, 0
	s_mov_b32 s25, 0xffff0000
	v_cndmask_b32_e64 v229, v229, v64, s[24:25]
	global_atomic_add_f32 v[230:231], v229, off
.LBB0_806:
	v_add_co_u32_e32 v68, vcc, 0x80000, v134
	s_mov_b64 s[24:25], 0x80000
	s_nop 0
	v_addc_co_u32_e32 v69, vcc, 0, v135, vcc
	s_waitcnt lgkmcnt(0)
	s_nop 1
	s_waitcnt vmcnt(15)
	v_mov_b32_e32 v64, v194
	v_mov_b32_e32 v65, v195
	v_mov_b32_e32 v66, v196
	v_mov_b32_e32 v67, v197
	v_lshl_add_u64 v[70:71], v[134:135], 0, s[24:25]
	s_nop 0
	v_lshlrev_b32_e32 v72, 16, v64
	v_and_b32_e32 v73, 0xffff0000, v64
	v_lshlrev_b32_e32 v64, 16, v65
	v_and_b32_e32 v65, 0xffff0000, v65
	v_lshlrev_b32_e32 v74, 16, v66
	v_and_b32_e32 v75, 0xffff0000, v66
	v_lshlrev_b32_e32 v66, 16, v67
	v_and_b32_e32 v67, 0xffff0000, v67
	v_pk_add_f32 v[64:65], v[62:63], v[64:65]
	v_pk_add_f32 v[72:73], v[60:61], v[72:73]
	v_pk_add_f32 v[66:67], v[58:59], v[66:67]
	v_pk_add_f32 v[74:75], v[56:57], v[74:75]
	v_cvt_pk_bf16_f32 v56, v72, v73
	v_cvt_pk_bf16_f32 v57, v64, v65
	v_mul_f32_e32 v73, v73, v73
	v_cvt_pk_bf16_f32 v58, v74, v75
	v_cvt_pk_bf16_f32 v59, v66, v67
	s_nop 1
	s_waitcnt vmcnt(14)
	v_mov_b32_e32 v60, v198
	v_mov_b32_e32 v61, v199
	v_mov_b32_e32 v62, v200
	v_mov_b32_e32 v63, v201
	v_mul_f32_e32 v65, v65, v65
	v_mul_f32_e32 v75, v75, v75
	v_fmac_f32_e32 v73, v72, v72
	v_fmac_f32_e32 v65, v64, v64
	v_mul_f32_e32 v67, v67, v67
	v_fmac_f32_e32 v75, v74, v74
	v_add_f32_e32 v64, v73, v65
	v_fmac_f32_e32 v67, v66, v66
	v_add_f32_e32 v64, v75, v64
	v_add_f32_e32 v72, v67, v64
	global_store_dwordx4 v[68:69], v[56:59], off
	s_nop 0
	v_lshlrev_b32_e32 v64, 16, v60
	v_and_b32_e32 v65, 0xffff0000, v60
	v_lshlrev_b32_e32 v60, 16, v61
	v_and_b32_e32 v61, 0xffff0000, v61
	v_lshlrev_b32_e32 v66, 16, v62
	v_and_b32_e32 v67, 0xffff0000, v62
	v_lshlrev_b32_e32 v62, 16, v63
	v_and_b32_e32 v63, 0xffff0000, v63
	v_pk_add_f32 v[54:55], v[54:55], v[60:61]
	v_pk_add_f32 v[52:53], v[52:53], v[64:65]
	v_pk_add_f32 v[60:61], v[50:51], v[62:63]
	v_pk_add_f32 v[62:63], v[48:49], v[66:67]
	v_mul_f32_e32 v48, v53, v53
	v_mul_f32_e32 v49, v55, v55
	v_mul_f32_e32 v50, v63, v63
	v_fmac_f32_e32 v48, v52, v52
	v_fmac_f32_e32 v49, v54, v54
	v_mul_f32_e32 v51, v61, v61
	v_fmac_f32_e32 v50, v62, v62
	v_add_f32_e32 v48, v48, v49
	v_add_f32_e32 v48, v50, v48
	v_fmac_f32_e32 v51, v60, v60
	v_add_f32_e32 v48, v51, v48
	v_add_f32_e32 v48, v72, v48
	ds_bpermute_b32 v49, v114, v48
	v_cvt_pk_bf16_f32 v50, v52, v53
	v_cvt_pk_bf16_f32 v51, v54, v55
	v_cvt_pk_bf16_f32 v52, v62, v63
	v_cvt_pk_bf16_f32 v53, v60, v61
	s_waitcnt lgkmcnt(0)
	v_add_f32_e32 v48, v48, v49
	ds_bpermute_b32 v49, v115, v48
	global_store_dwordx4 v[70:71], v[50:53], off offset:64
	s_waitcnt lgkmcnt(0)
	v_add_f32_e32 v48, v48, v49
	v_mov_b32_e32 v229, v48
; __device__ __forceinline__ u32x4 pack8(f32x4 a, f32x4 b) { u32x4 w; w.x = cvt_pk_bf16(a[0], a[1]); w.y = cvt_pk_bf16(a[2], a[3]); w.z = cvt_pk_bf16(b[0], b[1]); w.w = cvt_pk_bf16(b[2], b[3]); return w; }
;     __device__ __forceinline__ void operator()(const f32x4 (&acc)[2][2][4][2], const Unit& u, int wr, int wc, int fr, int fq) const {
;     ...
;                 const int row = row0 + ai * HALF + m * 16; const size_t off = (size_t)row * 2048 + col;
;                 float s = 0.f;
; #pragma unroll
;                 for (int bj = 0; bj < 2; ++bj) {
;                     f32x4 b0, b1;
;                     if (BASE_F32) { const float* bp = (const float*)base + off + bj * 32; b0 = *(const f32x4*)bp; b1 = *(const f32x4*)(bp + 4); }
;                     else { const u32x4 w = *(const u32x4*)((const bf16_t*)base + off + bj * 32);
;                         b0 = (f32x4){__uint_as_float(w.x << 16), __uint_as_float(w.x & 0xffff0000u), __uint_as_float(w.y << 16), __uint_as_float(w.y & 0xffff0000u)};
;                         b1 = (f32x4){__uint_as_float(w.z << 16), __uint_as_float(w.z & 0xffff0000u), __uint_as_float(w.w << 16), __uint_as_float(w.w & 0xffff0000u)}; }
;                     const f32x4 h0 = b0 + acc[ai][bj][m][0], h1 = b1 + acc[ai][bj][m][1];
;                     s += (h0[0] * h0[0] + h0[1] * h0[1]) + (h0[2] * h0[2] + h0[3] * h0[3]) + (h1[0] * h1[0] + h1[1] * h1[1]) + (h1[2] * h1[2] + h1[3] * h1[3]);
;                     *(u32x4*)(H + off + bj * 32) = pack8(h0, h1);
;                 }
;                 s += __shfl_xor(s, 16); s += __shfl_xor(s, 32);
;                 if (fq == 0) __hip_atomic_fetch_add(ss + row, s, __ATOMIC_RELAXED, __HIP_MEMORY_SCOPE_AGENT);
.LBB0_808:
	v_add_co_u32_e32 v52, vcc, 0x90000, v134
	s_mov_b64 s[24:25], 0x90000
	s_nop 0
	v_addc_co_u32_e32 v53, vcc, 0, v135, vcc
	s_waitcnt lgkmcnt(0)
	s_nop 1
	s_waitcnt vmcnt(15)
	v_mov_b32_e32 v48, v212
	v_mov_b32_e32 v49, v213
	v_mov_b32_e32 v50, v214
	v_mov_b32_e32 v51, v215
	v_lshl_add_u64 v[54:55], v[134:135], 0, s[24:25]
	s_nop 0
	v_lshlrev_b32_e32 v56, 16, v48
	v_and_b32_e32 v57, 0xffff0000, v48
	v_lshlrev_b32_e32 v48, 16, v49
	v_and_b32_e32 v49, 0xffff0000, v49
	v_lshlrev_b32_e32 v58, 16, v50
	v_and_b32_e32 v59, 0xffff0000, v50
	v_lshlrev_b32_e32 v50, 16, v51
	v_and_b32_e32 v51, 0xffff0000, v51
	v_pk_add_f32 v[48:49], v[46:47], v[48:49]
	v_pk_add_f32 v[56:57], v[44:45], v[56:57]
	v_pk_add_f32 v[50:51], v[42:43], v[50:51]
	v_pk_add_f32 v[58:59], v[40:41], v[58:59]
	v_cvt_pk_bf16_f32 v40, v56, v57
	v_cvt_pk_bf16_f32 v41, v48, v49
	v_mul_f32_e32 v57, v57, v57
	v_cvt_pk_bf16_f32 v42, v58, v59
	v_cvt_pk_bf16_f32 v43, v50, v51
	s_nop 1
	s_waitcnt vmcnt(14)
	v_mov_b32_e32 v44, v216
	v_mov_b32_e32 v45, v217
	v_mov_b32_e32 v46, v218
	v_mov_b32_e32 v47, v219
	v_mul_f32_e32 v49, v49, v49
	v_mul_f32_e32 v59, v59, v59
	v_fmac_f32_e32 v57, v56, v56
	v_fmac_f32_e32 v49, v48, v48
	v_mul_f32_e32 v51, v51, v51
	v_fmac_f32_e32 v59, v58, v58
	v_add_f32_e32 v48, v57, v49
	v_fmac_f32_e32 v51, v50, v50
	v_add_f32_e32 v48, v59, v48
	v_add_f32_e32 v56, v51, v48
	global_store_dwordx4 v[52:53], v[40:43], off
	s_nop 0
	v_lshlrev_b32_e32 v48, 16, v44
	v_and_b32_e32 v49, 0xffff0000, v44
	v_lshlrev_b32_e32 v44, 16, v45
	v_and_b32_e32 v45, 0xffff0000, v45
	v_lshlrev_b32_e32 v50, 16, v46
	v_and_b32_e32 v51, 0xffff0000, v46
	v_lshlrev_b32_e32 v46, 16, v47
	v_and_b32_e32 v47, 0xffff0000, v47
	v_pk_add_f32 v[38:39], v[38:39], v[44:45]
	v_pk_add_f32 v[36:37], v[36:37], v[48:49]
	v_pk_add_f32 v[44:45], v[34:35], v[46:47]
	v_pk_add_f32 v[46:47], v[32:33], v[50:51]
	v_mul_f32_e32 v32, v37, v37
	v_mul_f32_e32 v33, v39, v39
	v_mul_f32_e32 v34, v47, v47
	v_fmac_f32_e32 v32, v36, v36
	v_fmac_f32_e32 v33, v38, v38
	v_mul_f32_e32 v35, v45, v45
	v_fmac_f32_e32 v34, v46, v46
	v_add_f32_e32 v32, v32, v33
	v_add_f32_e32 v32, v34, v32
	v_fmac_f32_e32 v35, v44, v44
	v_add_f32_e32 v32, v35, v32
	v_add_f32_e32 v32, v56, v32
	ds_bpermute_b32 v33, v114, v32
	v_cvt_pk_bf16_f32 v34, v36, v37
	v_cvt_pk_bf16_f32 v35, v38, v39
	v_cvt_pk_bf16_f32 v36, v46, v47
	v_cvt_pk_bf16_f32 v37, v44, v45
	s_waitcnt lgkmcnt(0)
	v_add_f32_e32 v32, v32, v33
	ds_bpermute_b32 v33, v115, v32
	global_store_dwordx4 v[54:55], v[34:37], off offset:64
	s_waitcnt lgkmcnt(0)
	v_add_f32_e32 v32, v32, v33
	s_mov_b32 s24, 0xffff0000
	s_mov_b32 s25, 0
	v_cndmask_b32_e64 v229, v229, v32, s[24:25]
.LBB0_810:
	v_add_co_u32_e32 v36, vcc, 0xa0000, v134
	s_mov_b64 s[24:25], 0xa0000
	s_nop 0
	v_addc_co_u32_e32 v37, vcc, 0, v135, vcc
	s_waitcnt lgkmcnt(0)
	s_nop 1
	s_waitcnt vmcnt(14)
	v_mov_b32_e32 v32, v154
	v_mov_b32_e32 v33, v155
	v_mov_b32_e32 v34, v156
	v_mov_b32_e32 v35, v157
	v_lshl_add_u64 v[38:39], v[134:135], 0, s[24:25]
	s_nop 0
	v_lshlrev_b32_e32 v40, 16, v32
	v_and_b32_e32 v41, 0xffff0000, v32
	v_lshlrev_b32_e32 v32, 16, v33
	v_and_b32_e32 v33, 0xffff0000, v33
	v_lshlrev_b32_e32 v42, 16, v34
	v_and_b32_e32 v43, 0xffff0000, v34
	v_lshlrev_b32_e32 v34, 16, v35
	v_and_b32_e32 v35, 0xffff0000, v35
	v_pk_add_f32 v[32:33], v[30:31], v[32:33]
	v_pk_add_f32 v[40:41], v[28:29], v[40:41]
	v_pk_add_f32 v[34:35], v[26:27], v[34:35]
	v_pk_add_f32 v[42:43], v[24:25], v[42:43]
	v_cvt_pk_bf16_f32 v24, v40, v41
	v_cvt_pk_bf16_f32 v25, v32, v33
	v_mul_f32_e32 v41, v41, v41
	v_cvt_pk_bf16_f32 v26, v42, v43
	v_cvt_pk_bf16_f32 v27, v34, v35
	s_nop 1
	s_waitcnt vmcnt(13)
	v_mov_b32_e32 v28, v158
	v_mov_b32_e32 v29, v159
	v_mov_b32_e32 v30, v160
	v_mov_b32_e32 v31, v161
	v_mul_f32_e32 v33, v33, v33
	v_mul_f32_e32 v43, v43, v43
	v_fmac_f32_e32 v41, v40, v40
	v_fmac_f32_e32 v33, v32, v32
	v_mul_f32_e32 v35, v35, v35
	v_fmac_f32_e32 v43, v42, v42
	v_add_f32_e32 v32, v41, v33
	v_fmac_f32_e32 v35, v34, v34
	v_add_f32_e32 v32, v43, v32
	v_add_f32_e32 v40, v35, v32
	global_store_dwordx4 v[36:37], v[24:27], off
	s_nop 0
	v_lshlrev_b32_e32 v32, 16, v28
	v_and_b32_e32 v33, 0xffff0000, v28
	v_lshlrev_b32_e32 v28, 16, v29
	v_and_b32_e32 v29, 0xffff0000, v29
	v_lshlrev_b32_e32 v34, 16, v30
	v_and_b32_e32 v35, 0xffff0000, v30
	v_lshlrev_b32_e32 v30, 16, v31
	v_and_b32_e32 v31, 0xffff0000, v31
	v_pk_add_f32 v[22:23], v[22:23], v[28:29]
	v_pk_add_f32 v[20:21], v[20:21], v[32:33]
	v_pk_add_f32 v[28:29], v[18:19], v[30:31]
	v_pk_add_f32 v[30:31], v[16:17], v[34:35]
	v_mul_f32_e32 v16, v21, v21
	v_mul_f32_e32 v17, v23, v23
	v_mul_f32_e32 v18, v31, v31
	v_fmac_f32_e32 v16, v20, v20
	v_fmac_f32_e32 v17, v22, v22
	v_mul_f32_e32 v19, v29, v29
	v_fmac_f32_e32 v18, v30, v30
	v_add_f32_e32 v16, v16, v17
	v_add_f32_e32 v16, v18, v16
	v_fmac_f32_e32 v19, v28, v28
	v_add_f32_e32 v16, v19, v16
	v_add_f32_e32 v16, v40, v16
	ds_bpermute_b32 v17, v114, v16
	v_cvt_pk_bf16_f32 v18, v20, v21
	v_cvt_pk_bf16_f32 v19, v22, v23
	v_cvt_pk_bf16_f32 v20, v30, v31
	v_cvt_pk_bf16_f32 v21, v28, v29
	s_waitcnt lgkmcnt(0)
	v_add_f32_e32 v16, v16, v17
	ds_bpermute_b32 v17, v115, v16
	global_store_dwordx4 v[38:39], v[18:21], off offset:64
	s_waitcnt lgkmcnt(0)
	v_add_f32_e32 v16, v16, v17
	s_mov_b32 s24, 0
	s_mov_b32 s25, 0xffff
	v_cndmask_b32_e64 v229, v229, v16, s[24:25]
; #define PG8_BAR __builtin_amdgcn_s_barrier()
; template <class Epi, class Sched, bool ALIGN_EPI = false, bool SP2 = false>
; __device__ __forceinline__ void gemm_phase(PG8_LAS unsigned char* lds, const Gemm g, const Sched& S, const Epi& E) {
;     ...
;         if (!has_next) break;
; #pragma unroll
;         for (int a = 0; a < 2; ++a)
; #pragma unroll
;             for (int b = 0; b < 2; ++b)
; #pragma unroll
;                 for (int m = 0; m < 4; ++m)
; #pragma unroll
;                     for (int n = 0; n < 2; ++n) acc[a][b][m][n] = (f32x4){0.f, 0.f, 0.f, 0.f};
;         cur = nxt; cA = nA; cB = nB; st = nst; ++ui;
;         if constexpr (ALIGN_EPI) { if (wr == 1) PG8_BAR; }
;     __device__ __forceinline__ void operator()(const f32x4 (&acc)[2][2][4][2], const Unit& u, int wr, int wc, int fr, int fq) const {
;     ...
;                 const int row = row0 + ai * HALF + m * 16; const size_t off = (size_t)row * 2048 + col;
;                 float s = 0.f;
; #pragma unroll
;                 for (int bj = 0; bj < 2; ++bj) {
;                     f32x4 b0, b1;
;                     if (BASE_F32) { const float* bp = (const float*)base + off + bj * 32; b0 = *(const f32x4*)bp; b1 = *(const f32x4*)(bp + 4); }
;                     else { const u32x4 w = *(const u32x4*)((const bf16_t*)base + off + bj * 32);
;                         b0 = (f32x4){__uint_as_float(w.x << 16), __uint_as_float(w.x & 0xffff0000u), __uint_as_float(w.y << 16), __uint_as_float(w.y & 0xffff0000u)};
;                         b1 = (f32x4){__uint_as_float(w.z << 16), __uint_as_float(w.z & 0xffff0000u), __uint_as_float(w.w << 16), __uint_as_float(w.w & 0xffff0000u)}; }
;                     const f32x4 h0 = b0 + acc[ai][bj][m][0], h1 = b1 + acc[ai][bj][m][1];
;                     s += (h0[0] * h0[0] + h0[1] * h0[1]) + (h0[2] * h0[2] + h0[3] * h0[3]) + (h1[0] * h1[0] + h1[1] * h1[1]) + (h1[2] * h1[2] + h1[3] * h1[3]);
;                     *(u32x4*)(H + off + bj * 32) = pack8(h0, h1);
;                 }
;                 s += __shfl_xor(s, 16); s += __shfl_xor(s, 32);
;                 if (fq == 0) __hip_atomic_fetch_add(ss + row, s, __ATOMIC_RELAXED, __HIP_MEMORY_SCOPE_AGENT);
;                 if (m & 1) asm volatile("" ::: "memory");
;             }
.LBB0_812:
	v_add_co_u32_e32 v20, vcc, 0xb0000, v134
	s_mov_b64 s[24:25], 0xb0000
	s_nop 0
	v_addc_co_u32_e32 v21, vcc, 0, v135, vcc
	s_waitcnt lgkmcnt(0)
	s_nop 1
	s_waitcnt vmcnt(13)
	v_mov_b32_e32 v16, v162
	v_mov_b32_e32 v17, v163
	v_mov_b32_e32 v18, v164
	v_mov_b32_e32 v19, v165
	v_lshl_add_u64 v[22:23], v[134:135], 0, s[24:25]
	s_nop 0
	v_lshlrev_b32_e32 v24, 16, v16
	v_and_b32_e32 v25, 0xffff0000, v16
	v_lshlrev_b32_e32 v16, 16, v17
	v_and_b32_e32 v17, 0xffff0000, v17
	v_lshlrev_b32_e32 v26, 16, v18
	v_and_b32_e32 v27, 0xffff0000, v18
	v_lshlrev_b32_e32 v18, 16, v19
	v_and_b32_e32 v19, 0xffff0000, v19
	v_pk_add_f32 v[16:17], v[14:15], v[16:17]
	v_pk_add_f32 v[24:25], v[12:13], v[24:25]
	v_pk_add_f32 v[18:19], v[10:11], v[18:19]
	v_pk_add_f32 v[26:27], v[8:9], v[26:27]
	v_cvt_pk_bf16_f32 v8, v24, v25
	v_cvt_pk_bf16_f32 v9, v16, v17
	v_mul_f32_e32 v25, v25, v25
	v_cvt_pk_bf16_f32 v10, v26, v27
	v_cvt_pk_bf16_f32 v11, v18, v19
	s_nop 1
	s_waitcnt vmcnt(12)
	v_mov_b32_e32 v12, v166
	v_mov_b32_e32 v13, v167
	v_mov_b32_e32 v14, v168
	v_mov_b32_e32 v15, v169
	v_mul_f32_e32 v17, v17, v17
	v_mul_f32_e32 v27, v27, v27
	v_fmac_f32_e32 v25, v24, v24
	v_fmac_f32_e32 v17, v16, v16
	v_mul_f32_e32 v19, v19, v19
	v_fmac_f32_e32 v27, v26, v26
	v_add_f32_e32 v16, v25, v17
	v_fmac_f32_e32 v19, v18, v18
	v_add_f32_e32 v16, v27, v16
	v_add_f32_e32 v24, v19, v16
	global_store_dwordx4 v[20:21], v[8:11], off
	s_nop 0
	v_lshlrev_b32_e32 v16, 16, v12
	v_and_b32_e32 v17, 0xffff0000, v12
	v_lshlrev_b32_e32 v12, 16, v13
	v_and_b32_e32 v13, 0xffff0000, v13
	v_lshlrev_b32_e32 v18, 16, v14
	v_and_b32_e32 v19, 0xffff0000, v14
	v_lshlrev_b32_e32 v14, 16, v15
	v_and_b32_e32 v15, 0xffff0000, v15
	v_pk_add_f32 v[6:7], v[6:7], v[12:13]
	v_pk_add_f32 v[4:5], v[4:5], v[16:17]
	v_pk_add_f32 v[12:13], v[2:3], v[14:15]
	v_pk_add_f32 v[14:15], v[0:1], v[18:19]
	v_mul_f32_e32 v0, v5, v5
	v_mul_f32_e32 v1, v7, v7
	v_mul_f32_e32 v2, v15, v15
	v_fmac_f32_e32 v0, v4, v4
	v_fmac_f32_e32 v1, v6, v6
	v_mul_f32_e32 v3, v13, v13
	v_fmac_f32_e32 v2, v14, v14
	v_add_f32_e32 v0, v0, v1
	v_add_f32_e32 v0, v2, v0
	v_fmac_f32_e32 v3, v12, v12
	v_add_f32_e32 v0, v3, v0
	v_add_f32_e32 v0, v24, v0
	ds_bpermute_b32 v1, v114, v0
	v_cvt_pk_bf16_f32 v2, v4, v5
	v_cvt_pk_bf16_f32 v3, v6, v7
	v_cvt_pk_bf16_f32 v4, v14, v15
	v_cvt_pk_bf16_f32 v5, v12, v13
	s_waitcnt lgkmcnt(0)
	v_add_f32_e32 v0, v0, v1
	ds_bpermute_b32 v1, v115, v0
	global_store_dwordx4 v[22:23], v[2:5], off offset:64
	s_waitcnt lgkmcnt(0)
	v_add_f32_e32 v0, v0, v1
	s_mov_b32 s24, 0
	s_mov_b32 s25, 0xffff0000
	v_cndmask_b32_e64 v229, v229, v0, s[24:25]
	global_atomic_add_f32 v[230:231], v229, off offset:512
.LBB0_814:
	s_andn2_b64 vcc, exec, s[4:5]
	s_mov_b64 s[4:5], -1
	s_cbranch_vccnz .LBB0_783
	s_andn2_b64 vcc, exec, s[6:7]
	s_cbranch_vccnz .LBB0_782
	s_barrier
	s_branch .LBB0_782
